# MFMA section entry: redundant lgkmcnt wait after the opening barrier removed; LDS-DMA m0 hazard slots filled by the address add instead of a nop
# baseline (speedup 1.0000x reference)
.LBB0_280:
	v_mov_b32_e32 v133, v0
	v_lshl_add_u64 v[10:11], s[30:31], 0, v[132:133]
	v_mov_b32_e32 v137, v0
	v_lshl_add_u64 v[12:13], s[30:31], 0, v[136:137]
	v_mov_b32_e32 v131, v0
	s_add_i32 m0, s44, 0x18000
	v_lshl_add_u64 v[10:11], v[10:11], 0, s[96:97]
	v_lshl_add_u64 v[14:15], s[28:29], 0, v[130:131]
	v_mov_b32_e32 v135, v0
	s_waitcnt vmcnt(2)
	s_barrier
	global_load_lds_dwordx4 v[10:11], off
	v_lshl_add_u64 v[10:11], v[12:13], 0, s[96:97]
	s_add_i32 m0, s44, 0x1a000
	s_add_i32 s47, s44, 0x8000
	s_add_i32 s48, s44, 0xa000
	v_lshl_add_u64 v[16:17], s[28:29], 0, v[134:135]
	global_load_lds_dwordx4 v[10:11], off
	v_lshl_add_u64 v[10:11], v[14:15], 0, s[96:97]
	s_mov_b32 m0, s47
	s_add_u32 s12, s30, 0x40080
	global_load_lds_dwordx4 v[10:11], off
	v_lshl_add_u64 v[10:11], v[16:17], 0, s[96:97]
	s_mov_b32 m0, s48
	s_addc_u32 s13, s31, 0
	global_load_lds_dwordx4 v[10:11], off
	s_add_i32 m0, s44, 0x1c000
	v_lshl_add_u64 v[10:11], s[12:13], 0, v[132:133]
	global_load_lds_dwordx4 v[10:11], off
	s_add_i32 m0, s44, 0x1e000
	v_lshl_add_u64 v[10:11], s[12:13], 0, v[136:137]
	global_load_lds_dwordx4 v[10:11], off
	s_waitcnt vmcnt(6)
	s_barrier
	s_and_saveexec_b64 s[12:13], s[4:5]
	s_cbranch_execz .LBB0_282
	v_cvt_f32_u32_e32 v162, v160
	v_cvt_f32_i32_e32 v1, v161
	v_fmamk_f32 v5, v162, 0x34800000, v228
	v_rsq_f32_e32 v5, v5
	v_lshl_add_u32 v9, v234, 2, 0
	v_add_u32_e32 v9, 0x21000, v9
	ds_write2st64_b32 v9, v1, v5 offset1:4

.LBB0_287:
	s_ashr_i32 s21, s20, 31
	s_lshl_b64 s[22:23], s[20:21], 19
	s_add_u32 s22, s80, s22
	s_addc_u32 s23, s81, s23
	s_and_b64 s[24:25], s[6:7], exec
	s_cselect_b32 s21, s23, s29
	s_cselect_b32 s36, s22, s28
	s_ashr_i32 s19, s18, 31
	s_lshl_b64 s[24:25], s[18:19], 19
	s_add_u32 s24, s40, s24
	s_addc_u32 s25, s41, s25
	s_and_b64 s[34:35], s[6:7], exec
	s_cselect_b32 s19, s25, s31
	s_cselect_b32 s37, s24, s30
	s_add_u32 s38, s30, 0x100
	s_addc_u32 s39, s31, 0
	s_add_u32 s28, s28, 0x40080
	s_addc_u32 s29, s29, 0
	s_mov_b32 s55, -2
	s_add_u32 s30, s28, 0xfffc0080
	s_addc_u32 s31, s29, -1
	s_add_i32 s56, 0, 0x10000
	s_cmp_eq_u32 s55, 12
	s_cselect_b32 s35, s21, s31
	s_cselect_b32 s34, s36, s30
	s_cselect_b32 s31, s19, s39
	s_cselect_b32 s30, s37, s38
	s_add_i32 s58, 0, 0x14000
	v_add_u32_e32 v166, s56, v147
	v_add_u32_e32 v182, s58, v147
	ds_read_b128 v[142:145], v166
	ds_read_b128 v[158:161], v166 offset:1024
	ds_read_b128 v[162:165], v166 offset:2048
	ds_read_b128 v[166:169], v166 offset:3072
	ds_read_b128 v[170:173], v182
	ds_read_b128 v[174:177], v182 offset:1024
	ds_read_b128 v[178:181], v182 offset:2048
	ds_read_b128 v[182:185], v182 offset:3072
	v_lshl_add_u64 v[224:225], s[28:29], 0, v[140:141]
	s_add_i32 m0, s44, 0xc000
	ds_read_b128 v[186:189], v157
	ds_read_b128 v[190:193], v157 offset:1024
	ds_read_b128 v[194:197], v157 offset:2048
	ds_read_b128 v[198:201], v157 offset:3072
	ds_read_b128 v[202:205], v157 offset:4096
	ds_read_b128 v[206:209], v157 offset:5120
	ds_read_b128 v[220:223], v157 offset:6144
	ds_read_b128 v[236:239], v157 offset:7168
	global_load_lds_dwordx4 v[224:225], off
	s_add_i32 m0, s44, 0xe000
	v_lshl_add_u64 v[224:225], s[28:29], 0, v[138:139]
	global_load_lds_dwordx4 v[224:225], off
	s_branch .Lpadj_0
	s_nop 0
	s_nop 0
	s_nop 0
	s_nop 0
	s_nop 0
.Lpadj_0:
	s_waitcnt vmcnt(8)
	s_waitcnt lgkmcnt(0)
	s_barrier
	v_mfma_f32_16x16x32_bf16 v[126:129], v[142:145], v[186:189], 0
	v_mfma_f32_16x16x32_bf16 v[122:125], v[162:165], v[186:189], 0
	v_mfma_f32_16x16x32_bf16 v[110:113], v[142:145], v[194:197], 0
	v_mfma_f32_16x16x32_bf16 v[106:109], v[162:165], v[194:197], 0
	v_mfma_f32_16x16x32_bf16 v[94:97], v[142:145], v[202:205], 0
	v_mfma_f32_16x16x32_bf16 v[90:93], v[162:165], v[202:205], 0
	v_mfma_f32_16x16x32_bf16 v[78:81], v[142:145], v[220:223], 0
	v_mfma_f32_16x16x32_bf16 v[74:77], v[162:165], v[220:223], 0
	v_mfma_f32_16x16x32_bf16 v[126:129], v[158:161], v[190:193], v[126:129]
	v_mfma_f32_16x16x32_bf16 v[122:125], v[166:169], v[190:193], v[122:125]
	v_mfma_f32_16x16x32_bf16 v[110:113], v[158:161], v[198:201], v[110:113]
	v_mfma_f32_16x16x32_bf16 v[106:109], v[166:169], v[198:201], v[106:109]
	v_mfma_f32_16x16x32_bf16 v[94:97], v[158:161], v[206:209], v[94:97]
	v_mfma_f32_16x16x32_bf16 v[90:93], v[166:169], v[206:209], v[90:93]
	v_mfma_f32_16x16x32_bf16 v[78:81], v[158:161], v[236:239], v[78:81]
	v_mfma_f32_16x16x32_bf16 v[74:77], v[166:169], v[236:239], v[74:77]
	v_mfma_f32_16x16x32_bf16 v[118:121], v[170:173], v[186:189], 0
	v_mfma_f32_16x16x32_bf16 v[114:117], v[178:181], v[186:189], 0
	v_mfma_f32_16x16x32_bf16 v[102:105], v[170:173], v[194:197], 0
	v_mfma_f32_16x16x32_bf16 v[98:101], v[178:181], v[194:197], 0
	v_mfma_f32_16x16x32_bf16 v[86:89], v[170:173], v[202:205], 0
	v_mfma_f32_16x16x32_bf16 v[82:85], v[178:181], v[202:205], 0
	v_mfma_f32_16x16x32_bf16 v[70:73], v[170:173], v[220:223], 0
	v_mfma_f32_16x16x32_bf16 v[66:69], v[178:181], v[220:223], 0
	v_mfma_f32_16x16x32_bf16 v[118:121], v[174:177], v[190:193], v[118:121]
	v_mfma_f32_16x16x32_bf16 v[114:117], v[182:185], v[190:193], v[114:117]
	v_mfma_f32_16x16x32_bf16 v[102:105], v[174:177], v[198:201], v[102:105]
	v_mfma_f32_16x16x32_bf16 v[98:101], v[182:185], v[198:201], v[98:101]
	v_mfma_f32_16x16x32_bf16 v[86:89], v[174:177], v[206:209], v[86:89]
	v_mfma_f32_16x16x32_bf16 v[82:85], v[182:185], v[206:209], v[82:85]
	v_mfma_f32_16x16x32_bf16 v[70:73], v[174:177], v[236:239], v[70:73]
	v_mfma_f32_16x16x32_bf16 v[66:69], v[182:185], v[236:239], v[66:69]
	s_barrier
	s_add_i32 s56, s56, s27
	v_lshl_add_u64 v[224:225], s[30:31], 0, v[132:133]
	s_mov_b32 m0, s56
	ds_read_b128 v[186:189], v157 offset:16384
	ds_read_b128 v[190:193], v157 offset:17408
	ds_read_b128 v[194:197], v157 offset:18432
	ds_read_b128 v[198:201], v157 offset:19456
	ds_read_b128 v[202:205], v157 offset:20480
	ds_read_b128 v[206:209], v157 offset:21504
	ds_read_b128 v[220:223], v157 offset:22528
	ds_read_b128 v[236:239], v157 offset:23552
	global_load_lds_dwordx4 v[224:225], off
	s_add_i32 m0, s56, 0x2000
	s_add_u32 s56, s30, 0x40000
	v_lshl_add_u64 v[230:231], s[30:31], 0, v[136:137]
	s_addc_u32 s57, s31, 0
	s_add_i32 s58, s58, s27
	global_load_lds_dwordx4 v[230:231], off
	v_lshl_add_u64 v[240:241], s[56:57], 0, v[132:133]
	s_mov_b32 m0, s58
	v_lshl_add_u64 v[242:243], s[34:35], 0, v[134:135]
	global_load_lds_dwordx4 v[240:241], off
	s_add_i32 m0, s58, 0x2000
	v_lshl_add_u64 v[240:241], s[56:57], 0, v[136:137]
	global_load_lds_dwordx4 v[240:241], off
	s_mov_b32 m0, s44
	v_lshl_add_u64 v[240:241], s[34:35], 0, v[130:131]
	global_load_lds_dwordx4 v[240:241], off
	s_mov_b32 m0, s45
	s_nop 0
	global_load_lds_dwordx4 v[242:243], off
	s_branch .Lpadj_1
	s_nop 0
	s_nop 0
	s_nop 0
	s_nop 0
	s_nop 0
.Lpadj_1:
	s_waitcnt vmcnt(8)
	s_waitcnt lgkmcnt(0)
	s_barrier
	v_mfma_f32_16x16x32_bf16 v[62:65], v[142:145], v[186:189], 0
	v_mfma_f32_16x16x32_bf16 v[58:61], v[162:165], v[186:189], 0
	v_mfma_f32_16x16x32_bf16 v[46:49], v[142:145], v[194:197], 0
	v_mfma_f32_16x16x32_bf16 v[42:45], v[162:165], v[194:197], 0
	v_mfma_f32_16x16x32_bf16 v[30:33], v[142:145], v[202:205], 0
	v_mfma_f32_16x16x32_bf16 v[26:29], v[162:165], v[202:205], 0
	v_mfma_f32_16x16x32_bf16 v[14:17], v[142:145], v[220:223], 0
	v_mfma_f32_16x16x32_bf16 v[10:13], v[162:165], v[220:223], 0
	v_mfma_f32_16x16x32_bf16 v[62:65], v[158:161], v[190:193], v[62:65]
	v_mfma_f32_16x16x32_bf16 v[58:61], v[166:169], v[190:193], v[58:61]
	v_mfma_f32_16x16x32_bf16 v[46:49], v[158:161], v[198:201], v[46:49]
	v_mfma_f32_16x16x32_bf16 v[42:45], v[166:169], v[198:201], v[42:45]
	v_mfma_f32_16x16x32_bf16 v[30:33], v[158:161], v[206:209], v[30:33]
	v_mfma_f32_16x16x32_bf16 v[26:29], v[166:169], v[206:209], v[26:29]
	v_mfma_f32_16x16x32_bf16 v[14:17], v[158:161], v[236:239], v[14:17]
	v_mfma_f32_16x16x32_bf16 v[10:13], v[166:169], v[236:239], v[10:13]
	v_mfma_f32_16x16x32_bf16 v[54:57], v[170:173], v[186:189], 0
	v_mfma_f32_16x16x32_bf16 v[50:53], v[178:181], v[186:189], 0
	v_mfma_f32_16x16x32_bf16 v[38:41], v[170:173], v[194:197], 0
	v_mfma_f32_16x16x32_bf16 v[34:37], v[178:181], v[194:197], 0
	v_mfma_f32_16x16x32_bf16 v[22:25], v[170:173], v[202:205], 0
	v_mfma_f32_16x16x32_bf16 v[18:21], v[178:181], v[202:205], 0
	v_mfma_f32_16x16x32_bf16 v[6:9], v[170:173], v[220:223], 0
	v_mfma_f32_16x16x32_bf16 v[2:5], v[178:181], v[220:223], 0
	v_mfma_f32_16x16x32_bf16 v[54:57], v[174:177], v[190:193], v[54:57]
	v_mfma_f32_16x16x32_bf16 v[50:53], v[182:185], v[190:193], v[50:53]
	v_mfma_f32_16x16x32_bf16 v[38:41], v[174:177], v[198:201], v[38:41]
	v_mfma_f32_16x16x32_bf16 v[34:37], v[182:185], v[198:201], v[34:37]
	v_mfma_f32_16x16x32_bf16 v[22:25], v[174:177], v[206:209], v[22:25]
	v_mfma_f32_16x16x32_bf16 v[18:21], v[182:185], v[206:209], v[18:21]
	v_mfma_f32_16x16x32_bf16 v[6:9], v[174:177], v[236:239], v[6:9]
	v_mfma_f32_16x16x32_bf16 v[2:5], v[182:185], v[236:239], v[2:5]
	s_barrier
	s_add_i32 s56, 0, 0x18000
	s_add_i32 s57, 0, 0x1c000
	v_add_u32_e32 v166, s56, v147
	v_add_u32_e32 v182, s57, v147
	ds_read_b128 v[142:145], v166
	ds_read_b128 v[158:161], v166 offset:1024
	ds_read_b128 v[162:165], v166 offset:2048
	ds_read_b128 v[166:169], v166 offset:3072
	ds_read_b128 v[170:173], v182
	ds_read_b128 v[174:177], v182 offset:1024
	ds_read_b128 v[178:181], v182 offset:2048
	ds_read_b128 v[182:185], v182 offset:3072
	s_add_u32 s34, s34, 0x40000
	s_addc_u32 s35, s35, 0
	s_mov_b32 m0, s43
	v_lshl_add_u64 v[244:245], s[34:35], 0, v[130:131]
	ds_read_b128 v[186:189], v157 offset:32768
	ds_read_b128 v[190:193], v157 offset:33792
	ds_read_b128 v[194:197], v157 offset:34816
	ds_read_b128 v[198:201], v157 offset:35840
	ds_read_b128 v[202:205], v157 offset:36864
	ds_read_b128 v[206:209], v157 offset:37888
	ds_read_b128 v[220:223], v157 offset:38912
	ds_read_b128 v[236:239], v157 offset:39936
	global_load_lds_dwordx4 v[244:245], off
	s_mov_b32 m0, s46
	v_lshl_add_u64 v[244:245], s[34:35], 0, v[134:135]
	global_load_lds_dwordx4 v[244:245], off
	s_branch .Lpadj_2
	s_nop 0
	s_nop 0
	s_nop 0
	s_nop 0
	s_nop 0
	s_nop 0
	s_nop 0
	s_nop 0
.Lpadj_2:
	s_waitcnt vmcnt(8)
	s_waitcnt lgkmcnt(0)
	s_barrier
	v_mfma_f32_16x16x32_bf16 v[126:129], v[142:145], v[186:189], v[126:129]
	v_mfma_f32_16x16x32_bf16 v[122:125], v[162:165], v[186:189], v[122:125]
	v_mfma_f32_16x16x32_bf16 v[110:113], v[142:145], v[194:197], v[110:113]
	v_mfma_f32_16x16x32_bf16 v[106:109], v[162:165], v[194:197], v[106:109]
	v_mfma_f32_16x16x32_bf16 v[94:97], v[142:145], v[202:205], v[94:97]
	v_mfma_f32_16x16x32_bf16 v[90:93], v[162:165], v[202:205], v[90:93]
	v_mfma_f32_16x16x32_bf16 v[78:81], v[142:145], v[220:223], v[78:81]
	v_mfma_f32_16x16x32_bf16 v[74:77], v[162:165], v[220:223], v[74:77]
	v_mfma_f32_16x16x32_bf16 v[126:129], v[158:161], v[190:193], v[126:129]
	v_mfma_f32_16x16x32_bf16 v[122:125], v[166:169], v[190:193], v[122:125]
	v_mfma_f32_16x16x32_bf16 v[110:113], v[158:161], v[198:201], v[110:113]
	v_mfma_f32_16x16x32_bf16 v[106:109], v[166:169], v[198:201], v[106:109]
	v_mfma_f32_16x16x32_bf16 v[94:97], v[158:161], v[206:209], v[94:97]
	v_mfma_f32_16x16x32_bf16 v[90:93], v[166:169], v[206:209], v[90:93]
	v_mfma_f32_16x16x32_bf16 v[78:81], v[158:161], v[236:239], v[78:81]
	v_mfma_f32_16x16x32_bf16 v[74:77], v[166:169], v[236:239], v[74:77]
	v_mfma_f32_16x16x32_bf16 v[118:121], v[170:173], v[186:189], v[118:121]
	v_mfma_f32_16x16x32_bf16 v[114:117], v[178:181], v[186:189], v[114:117]
	v_mfma_f32_16x16x32_bf16 v[102:105], v[170:173], v[194:197], v[102:105]
	v_mfma_f32_16x16x32_bf16 v[98:101], v[178:181], v[194:197], v[98:101]
	v_mfma_f32_16x16x32_bf16 v[86:89], v[170:173], v[202:205], v[86:89]
	v_mfma_f32_16x16x32_bf16 v[82:85], v[178:181], v[202:205], v[82:85]
	v_mfma_f32_16x16x32_bf16 v[70:73], v[170:173], v[220:223], v[70:73]
	v_mfma_f32_16x16x32_bf16 v[66:69], v[178:181], v[220:223], v[66:69]
	v_mfma_f32_16x16x32_bf16 v[118:121], v[174:177], v[190:193], v[118:121]
	v_mfma_f32_16x16x32_bf16 v[114:117], v[182:185], v[190:193], v[114:117]
	v_mfma_f32_16x16x32_bf16 v[102:105], v[174:177], v[198:201], v[102:105]
	v_mfma_f32_16x16x32_bf16 v[98:101], v[182:185], v[198:201], v[98:101]
	v_mfma_f32_16x16x32_bf16 v[86:89], v[174:177], v[206:209], v[86:89]
	v_mfma_f32_16x16x32_bf16 v[82:85], v[182:185], v[206:209], v[82:85]
	v_mfma_f32_16x16x32_bf16 v[70:73], v[174:177], v[236:239], v[70:73]
	v_mfma_f32_16x16x32_bf16 v[66:69], v[182:185], v[236:239], v[66:69]
	s_barrier
	s_add_i32 s34, s56, s27
	v_lshl_add_u64 v[224:225], v[224:225], 0, s[96:97]
	s_mov_b32 m0, s34
	ds_read_b128 v[186:189], v157 offset:49152
	ds_read_b128 v[190:193], v157 offset:50176
	ds_read_b128 v[194:197], v157 offset:51200
	ds_read_b128 v[198:201], v157 offset:52224
	ds_read_b128 v[202:205], v157 offset:53248
	ds_read_b128 v[206:209], v157 offset:54272
	ds_read_b128 v[220:223], v157 offset:55296
	ds_read_b128 v[236:239], v157 offset:56320
	global_load_lds_dwordx4 v[224:225], off
	s_add_i32 m0, s34, 0x2000
	s_add_u32 s30, s30, 0x40080
	v_lshl_add_u64 v[224:225], v[230:231], 0, s[96:97]
	s_addc_u32 s31, s31, 0
	s_add_i32 s34, s57, s27
	global_load_lds_dwordx4 v[224:225], off
	s_mov_b32 m0, s34
	v_lshl_add_u64 v[224:225], s[30:31], 0, v[132:133]
	global_load_lds_dwordx4 v[224:225], off
	s_add_i32 m0, s34, 0x2000
	v_lshl_add_u64 v[224:225], s[30:31], 0, v[136:137]
	global_load_lds_dwordx4 v[224:225], off
	s_mov_b32 m0, s47
	v_lshl_add_u64 v[224:225], v[240:241], 0, s[96:97]
	global_load_lds_dwordx4 v[224:225], off
	s_mov_b32 m0, s48
	v_lshl_add_u64 v[224:225], v[242:243], 0, s[96:97]
	global_load_lds_dwordx4 v[224:225], off
	s_branch .Lpadj_3
	s_nop 0
	s_nop 0
	s_nop 0
	s_nop 0
	s_nop 0
	s_nop 0
.Lpadj_3:
	s_waitcnt vmcnt(8)
	s_waitcnt lgkmcnt(0)
	s_barrier
	v_mfma_f32_16x16x32_bf16 v[62:65], v[142:145], v[186:189], v[62:65]
	v_mfma_f32_16x16x32_bf16 v[58:61], v[162:165], v[186:189], v[58:61]
	v_mfma_f32_16x16x32_bf16 v[46:49], v[142:145], v[194:197], v[46:49]
	v_mfma_f32_16x16x32_bf16 v[42:45], v[162:165], v[194:197], v[42:45]
	v_mfma_f32_16x16x32_bf16 v[30:33], v[142:145], v[202:205], v[30:33]
	v_mfma_f32_16x16x32_bf16 v[26:29], v[162:165], v[202:205], v[26:29]
	v_mfma_f32_16x16x32_bf16 v[14:17], v[142:145], v[220:223], v[14:17]
	v_mfma_f32_16x16x32_bf16 v[10:13], v[162:165], v[220:223], v[10:13]
	v_mfma_f32_16x16x32_bf16 v[62:65], v[158:161], v[190:193], v[62:65]
	v_mfma_f32_16x16x32_bf16 v[58:61], v[166:169], v[190:193], v[58:61]
	v_mfma_f32_16x16x32_bf16 v[46:49], v[158:161], v[198:201], v[46:49]
	v_mfma_f32_16x16x32_bf16 v[42:45], v[166:169], v[198:201], v[42:45]
	v_mfma_f32_16x16x32_bf16 v[30:33], v[158:161], v[206:209], v[30:33]
	v_mfma_f32_16x16x32_bf16 v[26:29], v[166:169], v[206:209], v[26:29]
	v_mfma_f32_16x16x32_bf16 v[14:17], v[158:161], v[236:239], v[14:17]
	v_mfma_f32_16x16x32_bf16 v[10:13], v[166:169], v[236:239], v[10:13]
	v_mfma_f32_16x16x32_bf16 v[54:57], v[170:173], v[186:189], v[54:57]
	v_mfma_f32_16x16x32_bf16 v[50:53], v[178:181], v[186:189], v[50:53]
	v_mfma_f32_16x16x32_bf16 v[38:41], v[170:173], v[194:197], v[38:41]
	v_mfma_f32_16x16x32_bf16 v[34:37], v[178:181], v[194:197], v[34:37]
	v_mfma_f32_16x16x32_bf16 v[22:25], v[170:173], v[202:205], v[22:25]
	v_mfma_f32_16x16x32_bf16 v[18:21], v[178:181], v[202:205], v[18:21]
	v_mfma_f32_16x16x32_bf16 v[6:9], v[170:173], v[220:223], v[6:9]
	v_mfma_f32_16x16x32_bf16 v[2:5], v[178:181], v[220:223], v[2:5]
	v_mfma_f32_16x16x32_bf16 v[54:57], v[174:177], v[190:193], v[54:57]
	v_mfma_f32_16x16x32_bf16 v[50:53], v[182:185], v[190:193], v[50:53]
	v_mfma_f32_16x16x32_bf16 v[38:41], v[174:177], v[198:201], v[38:41]
	v_mfma_f32_16x16x32_bf16 v[34:37], v[182:185], v[198:201], v[34:37]
	v_mfma_f32_16x16x32_bf16 v[22:25], v[174:177], v[206:209], v[22:25]
	v_mfma_f32_16x16x32_bf16 v[18:21], v[182:185], v[206:209], v[18:21]
	v_mfma_f32_16x16x32_bf16 v[6:9], v[174:177], v[236:239], v[6:9]
	v_mfma_f32_16x16x32_bf16 v[2:5], v[182:185], v[236:239], v[2:5]
	s_barrier
	s_add_i32 s55, s55, 2
	s_add_u32 s38, s38, 0x100
	s_addc_u32 s39, s39, 0
	s_add_u32 s28, s28, 0x100
	s_addc_u32 s29, s29, 0
	s_cmp_gt_u32 s55, 13
.LBB0_288:
	s_add_u32 s30, s28, 0xfffc0080
	s_addc_u32 s31, s29, -1
	s_add_i32 s56, 0, 0x10000
	s_cmp_eq_u32 s55, 12
	s_cselect_b32 s35, s21, s31
	s_cselect_b32 s34, s36, s30
	s_cselect_b32 s31, s19, s39
	s_cselect_b32 s30, s37, s38
	s_add_i32 s58, 0, 0x14000
	v_add_u32_e32 v166, s56, v147
	v_add_u32_e32 v182, s58, v147
	ds_read_b128 v[142:145], v166
	ds_read_b128 v[158:161], v166 offset:1024
	ds_read_b128 v[162:165], v166 offset:2048
	ds_read_b128 v[166:169], v166 offset:3072
	ds_read_b128 v[170:173], v182
	ds_read_b128 v[174:177], v182 offset:1024
	ds_read_b128 v[178:181], v182 offset:2048
	ds_read_b128 v[182:185], v182 offset:3072
	v_lshl_add_u64 v[224:225], s[28:29], 0, v[140:141]
	s_add_i32 m0, s44, 0xc000
	ds_read_b128 v[186:189], v157
	ds_read_b128 v[190:193], v157 offset:1024
	ds_read_b128 v[194:197], v157 offset:2048
	ds_read_b128 v[198:201], v157 offset:3072
	ds_read_b128 v[202:205], v157 offset:4096
	ds_read_b128 v[206:209], v157 offset:5120
	ds_read_b128 v[220:223], v157 offset:6144
	ds_read_b128 v[236:239], v157 offset:7168
	global_load_lds_dwordx4 v[224:225], off
	s_add_i32 m0, s44, 0xe000
	v_lshl_add_u64 v[224:225], s[28:29], 0, v[138:139]
	global_load_lds_dwordx4 v[224:225], off
	s_branch .Lpadj_4
	s_nop 0
	s_nop 0
	s_nop 0
	s_nop 0
	s_nop 0
	s_nop 0
	s_nop 0
	s_nop 0
	s_nop 0
.Lpadj_4:
	s_waitcnt vmcnt(8)
	s_waitcnt lgkmcnt(0)
	s_barrier
	v_mfma_f32_16x16x32_bf16 v[126:129], v[142:145], v[186:189], v[126:129]
	v_mfma_f32_16x16x32_bf16 v[122:125], v[162:165], v[186:189], v[122:125]
	v_mfma_f32_16x16x32_bf16 v[110:113], v[142:145], v[194:197], v[110:113]
	v_mfma_f32_16x16x32_bf16 v[106:109], v[162:165], v[194:197], v[106:109]
	v_mfma_f32_16x16x32_bf16 v[94:97], v[142:145], v[202:205], v[94:97]
	v_mfma_f32_16x16x32_bf16 v[90:93], v[162:165], v[202:205], v[90:93]
	v_mfma_f32_16x16x32_bf16 v[78:81], v[142:145], v[220:223], v[78:81]
	v_mfma_f32_16x16x32_bf16 v[74:77], v[162:165], v[220:223], v[74:77]
	v_mfma_f32_16x16x32_bf16 v[126:129], v[158:161], v[190:193], v[126:129]
	v_mfma_f32_16x16x32_bf16 v[122:125], v[166:169], v[190:193], v[122:125]
	v_mfma_f32_16x16x32_bf16 v[110:113], v[158:161], v[198:201], v[110:113]
	v_mfma_f32_16x16x32_bf16 v[106:109], v[166:169], v[198:201], v[106:109]
	v_mfma_f32_16x16x32_bf16 v[94:97], v[158:161], v[206:209], v[94:97]
	v_mfma_f32_16x16x32_bf16 v[90:93], v[166:169], v[206:209], v[90:93]
	v_mfma_f32_16x16x32_bf16 v[78:81], v[158:161], v[236:239], v[78:81]
	v_mfma_f32_16x16x32_bf16 v[74:77], v[166:169], v[236:239], v[74:77]
	v_mfma_f32_16x16x32_bf16 v[118:121], v[170:173], v[186:189], v[118:121]
	v_mfma_f32_16x16x32_bf16 v[114:117], v[178:181], v[186:189], v[114:117]
	v_mfma_f32_16x16x32_bf16 v[102:105], v[170:173], v[194:197], v[102:105]
	v_mfma_f32_16x16x32_bf16 v[98:101], v[178:181], v[194:197], v[98:101]
	v_mfma_f32_16x16x32_bf16 v[86:89], v[170:173], v[202:205], v[86:89]
	v_mfma_f32_16x16x32_bf16 v[82:85], v[178:181], v[202:205], v[82:85]
	v_mfma_f32_16x16x32_bf16 v[70:73], v[170:173], v[220:223], v[70:73]
	v_mfma_f32_16x16x32_bf16 v[66:69], v[178:181], v[220:223], v[66:69]
	v_mfma_f32_16x16x32_bf16 v[118:121], v[174:177], v[190:193], v[118:121]
	v_mfma_f32_16x16x32_bf16 v[114:117], v[182:185], v[190:193], v[114:117]
	v_mfma_f32_16x16x32_bf16 v[102:105], v[174:177], v[198:201], v[102:105]
	v_mfma_f32_16x16x32_bf16 v[98:101], v[182:185], v[198:201], v[98:101]
	v_mfma_f32_16x16x32_bf16 v[86:89], v[174:177], v[206:209], v[86:89]
	v_mfma_f32_16x16x32_bf16 v[82:85], v[182:185], v[206:209], v[82:85]
	v_mfma_f32_16x16x32_bf16 v[70:73], v[174:177], v[236:239], v[70:73]
	v_mfma_f32_16x16x32_bf16 v[66:69], v[182:185], v[236:239], v[66:69]
	s_barrier
	s_add_i32 s56, s56, s27
	v_lshl_add_u64 v[224:225], s[30:31], 0, v[132:133]
	s_mov_b32 m0, s56
	ds_read_b128 v[186:189], v157 offset:16384
	ds_read_b128 v[190:193], v157 offset:17408
	ds_read_b128 v[194:197], v157 offset:18432
	ds_read_b128 v[198:201], v157 offset:19456
	ds_read_b128 v[202:205], v157 offset:20480
	ds_read_b128 v[206:209], v157 offset:21504
	ds_read_b128 v[220:223], v157 offset:22528
	ds_read_b128 v[236:239], v157 offset:23552
	global_load_lds_dwordx4 v[224:225], off
	s_add_i32 m0, s56, 0x2000
	s_add_u32 s56, s30, 0x40000
	v_lshl_add_u64 v[230:231], s[30:31], 0, v[136:137]
	s_addc_u32 s57, s31, 0
	s_add_i32 s58, s58, s27
	global_load_lds_dwordx4 v[230:231], off
	v_lshl_add_u64 v[240:241], s[56:57], 0, v[132:133]
	s_mov_b32 m0, s58
	v_lshl_add_u64 v[242:243], s[34:35], 0, v[134:135]
	global_load_lds_dwordx4 v[240:241], off
	s_add_i32 m0, s58, 0x2000
	v_lshl_add_u64 v[240:241], s[56:57], 0, v[136:137]
	global_load_lds_dwordx4 v[240:241], off
	s_mov_b32 m0, s44
	v_lshl_add_u64 v[240:241], s[34:35], 0, v[130:131]
	global_load_lds_dwordx4 v[240:241], off
	s_mov_b32 m0, s45
	s_nop 0
	global_load_lds_dwordx4 v[242:243], off
	s_branch .Lpadj_5
	s_nop 0
	s_nop 0
	s_nop 0
	s_nop 0
	s_nop 0
.Lpadj_5:
	s_waitcnt vmcnt(8)
	s_waitcnt lgkmcnt(0)
	s_barrier
	v_mfma_f32_16x16x32_bf16 v[62:65], v[142:145], v[186:189], v[62:65]
	v_mfma_f32_16x16x32_bf16 v[58:61], v[162:165], v[186:189], v[58:61]
	v_mfma_f32_16x16x32_bf16 v[46:49], v[142:145], v[194:197], v[46:49]
	v_mfma_f32_16x16x32_bf16 v[42:45], v[162:165], v[194:197], v[42:45]
	v_mfma_f32_16x16x32_bf16 v[30:33], v[142:145], v[202:205], v[30:33]
	v_mfma_f32_16x16x32_bf16 v[26:29], v[162:165], v[202:205], v[26:29]
	v_mfma_f32_16x16x32_bf16 v[14:17], v[142:145], v[220:223], v[14:17]
	v_mfma_f32_16x16x32_bf16 v[10:13], v[162:165], v[220:223], v[10:13]
	v_mfma_f32_16x16x32_bf16 v[62:65], v[158:161], v[190:193], v[62:65]
	v_mfma_f32_16x16x32_bf16 v[58:61], v[166:169], v[190:193], v[58:61]
	v_mfma_f32_16x16x32_bf16 v[46:49], v[158:161], v[198:201], v[46:49]
	v_mfma_f32_16x16x32_bf16 v[42:45], v[166:169], v[198:201], v[42:45]
	v_mfma_f32_16x16x32_bf16 v[30:33], v[158:161], v[206:209], v[30:33]
	v_mfma_f32_16x16x32_bf16 v[26:29], v[166:169], v[206:209], v[26:29]
	v_mfma_f32_16x16x32_bf16 v[14:17], v[158:161], v[236:239], v[14:17]
	v_mfma_f32_16x16x32_bf16 v[10:13], v[166:169], v[236:239], v[10:13]
	v_mfma_f32_16x16x32_bf16 v[54:57], v[170:173], v[186:189], v[54:57]
	v_mfma_f32_16x16x32_bf16 v[50:53], v[178:181], v[186:189], v[50:53]
	v_mfma_f32_16x16x32_bf16 v[38:41], v[170:173], v[194:197], v[38:41]
	v_mfma_f32_16x16x32_bf16 v[34:37], v[178:181], v[194:197], v[34:37]
	v_mfma_f32_16x16x32_bf16 v[22:25], v[170:173], v[202:205], v[22:25]
	v_mfma_f32_16x16x32_bf16 v[18:21], v[178:181], v[202:205], v[18:21]
	v_mfma_f32_16x16x32_bf16 v[6:9], v[170:173], v[220:223], v[6:9]
	v_mfma_f32_16x16x32_bf16 v[2:5], v[178:181], v[220:223], v[2:5]
	v_mfma_f32_16x16x32_bf16 v[54:57], v[174:177], v[190:193], v[54:57]
	v_mfma_f32_16x16x32_bf16 v[50:53], v[182:185], v[190:193], v[50:53]
	v_mfma_f32_16x16x32_bf16 v[38:41], v[174:177], v[198:201], v[38:41]
	v_mfma_f32_16x16x32_bf16 v[34:37], v[182:185], v[198:201], v[34:37]
	v_mfma_f32_16x16x32_bf16 v[22:25], v[174:177], v[206:209], v[22:25]
	v_mfma_f32_16x16x32_bf16 v[18:21], v[182:185], v[206:209], v[18:21]
	v_mfma_f32_16x16x32_bf16 v[6:9], v[174:177], v[236:239], v[6:9]
	v_mfma_f32_16x16x32_bf16 v[2:5], v[182:185], v[236:239], v[2:5]
	s_barrier
	s_add_i32 s56, 0, 0x18000
	s_add_i32 s57, 0, 0x1c000
	v_add_u32_e32 v166, s56, v147
	v_add_u32_e32 v182, s57, v147
	ds_read_b128 v[142:145], v166
	ds_read_b128 v[158:161], v166 offset:1024
	ds_read_b128 v[162:165], v166 offset:2048
	ds_read_b128 v[166:169], v166 offset:3072
	ds_read_b128 v[170:173], v182
	ds_read_b128 v[174:177], v182 offset:1024
	ds_read_b128 v[178:181], v182 offset:2048
	ds_read_b128 v[182:185], v182 offset:3072
	s_add_u32 s34, s34, 0x40000
	s_addc_u32 s35, s35, 0
	s_mov_b32 m0, s43
	v_lshl_add_u64 v[244:245], s[34:35], 0, v[130:131]
	ds_read_b128 v[186:189], v157 offset:32768
	ds_read_b128 v[190:193], v157 offset:33792
	ds_read_b128 v[194:197], v157 offset:34816
	ds_read_b128 v[198:201], v157 offset:35840
	ds_read_b128 v[202:205], v157 offset:36864
	ds_read_b128 v[206:209], v157 offset:37888
	ds_read_b128 v[220:223], v157 offset:38912
	ds_read_b128 v[236:239], v157 offset:39936
	global_load_lds_dwordx4 v[244:245], off
	s_mov_b32 m0, s46
	v_lshl_add_u64 v[244:245], s[34:35], 0, v[134:135]
	global_load_lds_dwordx4 v[244:245], off
	s_branch .Lpadj_6
	s_nop 0
	s_nop 0
	s_nop 0
	s_nop 0
	s_nop 0
	s_nop 0
	s_nop 0
	s_nop 0

.Lpadj_7:
	s_waitcnt vmcnt(8)
	s_waitcnt lgkmcnt(0)
	s_barrier
	v_mfma_f32_16x16x32_bf16 v[62:65], v[142:145], v[186:189], v[62:65]
	v_mfma_f32_16x16x32_bf16 v[58:61], v[162:165], v[186:189], v[58:61]
	v_mfma_f32_16x16x32_bf16 v[46:49], v[142:145], v[194:197], v[46:49]
	v_mfma_f32_16x16x32_bf16 v[42:45], v[162:165], v[194:197], v[42:45]
	v_mfma_f32_16x16x32_bf16 v[30:33], v[142:145], v[202:205], v[30:33]
	v_mfma_f32_16x16x32_bf16 v[26:29], v[162:165], v[202:205], v[26:29]
	v_mfma_f32_16x16x32_bf16 v[14:17], v[142:145], v[220:223], v[14:17]
	v_mfma_f32_16x16x32_bf16 v[10:13], v[162:165], v[220:223], v[10:13]
	v_mfma_f32_16x16x32_bf16 v[62:65], v[158:161], v[190:193], v[62:65]
	v_mfma_f32_16x16x32_bf16 v[58:61], v[166:169], v[190:193], v[58:61]
	v_mfma_f32_16x16x32_bf16 v[46:49], v[158:161], v[198:201], v[46:49]
	v_mfma_f32_16x16x32_bf16 v[42:45], v[166:169], v[198:201], v[42:45]
	v_mfma_f32_16x16x32_bf16 v[30:33], v[158:161], v[206:209], v[30:33]
	v_mfma_f32_16x16x32_bf16 v[26:29], v[166:169], v[206:209], v[26:29]
	v_mfma_f32_16x16x32_bf16 v[14:17], v[158:161], v[236:239], v[14:17]
	v_mfma_f32_16x16x32_bf16 v[10:13], v[166:169], v[236:239], v[10:13]
	v_mfma_f32_16x16x32_bf16 v[54:57], v[170:173], v[186:189], v[54:57]
	v_mfma_f32_16x16x32_bf16 v[50:53], v[178:181], v[186:189], v[50:53]
	v_mfma_f32_16x16x32_bf16 v[38:41], v[170:173], v[194:197], v[38:41]
	v_mfma_f32_16x16x32_bf16 v[34:37], v[178:181], v[194:197], v[34:37]
	v_mfma_f32_16x16x32_bf16 v[22:25], v[170:173], v[202:205], v[22:25]
	v_mfma_f32_16x16x32_bf16 v[18:21], v[178:181], v[202:205], v[18:21]
	v_mfma_f32_16x16x32_bf16 v[6:9], v[170:173], v[220:223], v[6:9]
	v_mfma_f32_16x16x32_bf16 v[2:5], v[178:181], v[220:223], v[2:5]
	v_mfma_f32_16x16x32_bf16 v[54:57], v[174:177], v[190:193], v[54:57]
	v_mfma_f32_16x16x32_bf16 v[50:53], v[182:185], v[190:193], v[50:53]
	v_mfma_f32_16x16x32_bf16 v[38:41], v[174:177], v[198:201], v[38:41]
	v_mfma_f32_16x16x32_bf16 v[34:37], v[182:185], v[198:201], v[34:37]
	v_mfma_f32_16x16x32_bf16 v[22:25], v[174:177], v[206:209], v[22:25]
	v_mfma_f32_16x16x32_bf16 v[18:21], v[182:185], v[206:209], v[18:21]
	v_mfma_f32_16x16x32_bf16 v[6:9], v[174:177], v[236:239], v[6:9]
	v_mfma_f32_16x16x32_bf16 v[2:5], v[182:185], v[236:239], v[2:5]
	s_barrier
	s_add_i32 s55, s55, 2
	s_add_u32 s38, s38, 0x100
	s_addc_u32 s39, s39, 0
	s_add_u32 s28, s28, 0x100
	s_addc_u32 s29, s29, 0
	s_cmp_gt_u32 s55, 13
	s_cbranch_scc0 .LBB0_288
	s_and_b64 vcc, exec, s[12:13]
	s_cbranch_vccz .LBB0_291
	s_barrier

.LBB0_362:
	s_ashr_i32 s23, s22, 31
	s_lshl_b64 s[24:25], s[22:23], 19
	s_add_u32 s24, s80, s24
	s_addc_u32 s25, s81, s25
	s_and_b64 s[26:27], s[6:7], exec
	s_cselect_b32 s23, s25, s35
	s_cselect_b32 s39, s24, s34
	s_ashr_i32 s21, s20, 31
	s_lshl_b64 s[26:27], s[20:21], 19
	s_add_u32 s26, s45, s26
	s_addc_u32 s27, s46, s27
	s_and_b64 s[36:37], s[6:7], exec
	s_cselect_b32 s21, s27, s31
	s_cselect_b32 s40, s26, s30
	s_add_u32 s41, s30, 0x100
	s_addc_u32 s43, s31, 0
	s_add_u32 s30, s34, 0x40080
	s_addc_u32 s31, s35, 0
	s_mov_b32 s56, -2
	s_add_u32 s34, s30, 0xfffc0080
	s_addc_u32 s35, s31, -1
	s_add_i32 s57, 0, 0x10000
	s_cmp_eq_u32 s56, 12
	s_cselect_b32 s37, s23, s35
	s_cselect_b32 s36, s39, s34
	v_add_u32_e32 v146, s57, v155
	s_cselect_b32 s35, s21, s43
	s_cselect_b32 s34, s40, s41
	s_add_i32 s60, 0, 0x14000
	ds_read_b128 v[142:145], v146
	ds_read_b128 v[168:171], v146 offset:1024
	ds_read_b128 v[172:175], v146 offset:2048
	ds_read_b128 v[176:179], v146 offset:3072
	v_add_u32_e32 v146, s60, v155
	ds_read_b128 v[180:183], v146
	ds_read_b128 v[184:187], v146 offset:1024
	ds_read_b128 v[188:191], v146 offset:2048
	ds_read_b128 v[192:195], v146 offset:3072
	v_lshl_add_u64 v[146:147], s[30:31], 0, v[140:141]
	s_add_i32 m0, s48, 0xc000
	ds_read_b128 v[196:199], v157
	ds_read_b128 v[200:203], v157 offset:1024
	ds_read_b128 v[204:207], v157 offset:2048
	ds_read_b128 v[220:223], v157 offset:3072
	ds_read_b128 v[236:239], v157 offset:4096
	ds_read_b128 v[240:243], v157 offset:5120
	ds_read_b128 v[244:247], v157 offset:6144
	ds_read_b128 v[248:251], v157 offset:7168
	global_load_lds_dwordx4 v[146:147], off
	s_add_i32 m0, s48, 0xe000
	v_lshl_add_u64 v[146:147], s[30:31], 0, v[138:139]
	global_load_lds_dwordx4 v[146:147], off
	s_branch .Lpadj_8
	s_nop 0
	s_nop 0
	s_nop 0
	s_nop 0
	s_nop 0
	s_nop 0
	s_nop 0
.Lpadj_8:
	s_waitcnt vmcnt(8)
	s_waitcnt lgkmcnt(0)
	s_barrier
	v_mfma_f32_16x16x32_bf16 v[126:129], v[142:145], v[196:199], 0
	v_mfma_f32_16x16x32_bf16 v[118:121], v[172:175], v[196:199], 0
	v_mfma_f32_16x16x32_bf16 v[110:113], v[142:145], v[204:207], 0
	v_mfma_f32_16x16x32_bf16 v[102:105], v[172:175], v[204:207], 0
	v_mfma_f32_16x16x32_bf16 v[94:97], v[142:145], v[236:239], 0
	v_mfma_f32_16x16x32_bf16 v[86:89], v[172:175], v[236:239], 0
	v_mfma_f32_16x16x32_bf16 v[78:81], v[142:145], v[244:247], 0
	v_mfma_f32_16x16x32_bf16 v[70:73], v[172:175], v[244:247], 0
	v_mfma_f32_16x16x32_bf16 v[126:129], v[168:171], v[200:203], v[126:129]
	v_mfma_f32_16x16x32_bf16 v[118:121], v[176:179], v[200:203], v[118:121]
	v_mfma_f32_16x16x32_bf16 v[110:113], v[168:171], v[220:223], v[110:113]
	v_mfma_f32_16x16x32_bf16 v[102:105], v[176:179], v[220:223], v[102:105]
	v_mfma_f32_16x16x32_bf16 v[94:97], v[168:171], v[240:243], v[94:97]
	v_mfma_f32_16x16x32_bf16 v[86:89], v[176:179], v[240:243], v[86:89]
	v_mfma_f32_16x16x32_bf16 v[78:81], v[168:171], v[248:251], v[78:81]
	v_mfma_f32_16x16x32_bf16 v[70:73], v[176:179], v[248:251], v[70:73]
	v_mfma_f32_16x16x32_bf16 v[122:125], v[180:183], v[196:199], 0
	v_mfma_f32_16x16x32_bf16 v[114:117], v[188:191], v[196:199], 0
	v_mfma_f32_16x16x32_bf16 v[106:109], v[180:183], v[204:207], 0
	v_mfma_f32_16x16x32_bf16 v[98:101], v[188:191], v[204:207], 0
	v_mfma_f32_16x16x32_bf16 v[90:93], v[180:183], v[236:239], 0
	v_mfma_f32_16x16x32_bf16 v[82:85], v[188:191], v[236:239], 0
	v_mfma_f32_16x16x32_bf16 v[74:77], v[180:183], v[244:247], 0
	v_mfma_f32_16x16x32_bf16 v[66:69], v[188:191], v[244:247], 0
	v_mfma_f32_16x16x32_bf16 v[122:125], v[184:187], v[200:203], v[122:125]
	v_mfma_f32_16x16x32_bf16 v[114:117], v[192:195], v[200:203], v[114:117]
	v_mfma_f32_16x16x32_bf16 v[106:109], v[184:187], v[220:223], v[106:109]
	v_mfma_f32_16x16x32_bf16 v[98:101], v[192:195], v[220:223], v[98:101]
	v_mfma_f32_16x16x32_bf16 v[90:93], v[184:187], v[240:243], v[90:93]
	v_mfma_f32_16x16x32_bf16 v[82:85], v[192:195], v[240:243], v[82:85]
	v_mfma_f32_16x16x32_bf16 v[74:77], v[184:187], v[248:251], v[74:77]
	v_mfma_f32_16x16x32_bf16 v[66:69], v[192:195], v[248:251], v[66:69]
	s_barrier
	s_add_i32 s57, s57, s44
	v_lshl_add_u64 v[146:147], s[34:35], 0, v[134:135]
	s_mov_b32 m0, s57
	ds_read_b128 v[196:199], v157 offset:16384
	ds_read_b128 v[200:203], v157 offset:17408
	ds_read_b128 v[204:207], v157 offset:18432
	ds_read_b128 v[220:223], v157 offset:19456
	ds_read_b128 v[236:239], v157 offset:20480
	ds_read_b128 v[240:243], v157 offset:21504
	ds_read_b128 v[244:247], v157 offset:22528
	ds_read_b128 v[248:251], v157 offset:23552
	global_load_lds_dwordx4 v[146:147], off
	s_add_i32 m0, s57, 0x2000
	s_add_u32 s58, s34, 0x40000
	v_lshl_add_u64 v[208:209], s[34:35], 0, v[130:131]
	s_addc_u32 s59, s35, 0
	s_add_i32 s57, s60, s44
	global_load_lds_dwordx4 v[208:209], off
	v_lshl_add_u64 v[224:225], s[58:59], 0, v[134:135]
	s_mov_b32 m0, s57
	v_lshl_add_u64 v[230:231], s[36:37], 0, v[132:133]
	global_load_lds_dwordx4 v[224:225], off
	s_add_i32 m0, s57, 0x2000
	v_lshl_add_u64 v[224:225], s[58:59], 0, v[130:131]
	global_load_lds_dwordx4 v[224:225], off
	s_mov_b32 m0, s48
	v_lshl_add_u64 v[224:225], s[36:37], 0, v[136:137]
	global_load_lds_dwordx4 v[224:225], off
	s_mov_b32 m0, s49
	s_nop 0
	global_load_lds_dwordx4 v[230:231], off
	s_branch .Lpadj_9
	s_nop 0
	s_nop 0
	s_nop 0
	s_nop 0
	s_nop 0
.Lpadj_9:
	s_waitcnt vmcnt(8)
	s_waitcnt lgkmcnt(0)
	s_barrier
	v_mfma_f32_16x16x32_bf16 v[62:65], v[142:145], v[196:199], 0
	v_mfma_f32_16x16x32_bf16 v[54:57], v[172:175], v[196:199], 0
	v_mfma_f32_16x16x32_bf16 v[46:49], v[142:145], v[204:207], 0
	v_mfma_f32_16x16x32_bf16 v[38:41], v[172:175], v[204:207], 0
	v_mfma_f32_16x16x32_bf16 v[30:33], v[142:145], v[236:239], 0
	v_mfma_f32_16x16x32_bf16 v[22:25], v[172:175], v[236:239], 0
	v_mfma_f32_16x16x32_bf16 v[14:17], v[142:145], v[244:247], 0
	v_mfma_f32_16x16x32_bf16 v[6:9], v[172:175], v[244:247], 0
	v_mfma_f32_16x16x32_bf16 v[62:65], v[168:171], v[200:203], v[62:65]
	v_mfma_f32_16x16x32_bf16 v[54:57], v[176:179], v[200:203], v[54:57]
	v_mfma_f32_16x16x32_bf16 v[46:49], v[168:171], v[220:223], v[46:49]
	v_mfma_f32_16x16x32_bf16 v[38:41], v[176:179], v[220:223], v[38:41]
	v_mfma_f32_16x16x32_bf16 v[30:33], v[168:171], v[240:243], v[30:33]
	v_mfma_f32_16x16x32_bf16 v[22:25], v[176:179], v[240:243], v[22:25]
	v_mfma_f32_16x16x32_bf16 v[14:17], v[168:171], v[248:251], v[14:17]
	v_mfma_f32_16x16x32_bf16 v[6:9], v[176:179], v[248:251], v[6:9]
	v_mfma_f32_16x16x32_bf16 v[58:61], v[180:183], v[196:199], 0
	v_mfma_f32_16x16x32_bf16 v[50:53], v[188:191], v[196:199], 0
	v_mfma_f32_16x16x32_bf16 v[42:45], v[180:183], v[204:207], 0
	v_mfma_f32_16x16x32_bf16 v[34:37], v[188:191], v[204:207], 0
	v_mfma_f32_16x16x32_bf16 v[26:29], v[180:183], v[236:239], 0
	v_mfma_f32_16x16x32_bf16 v[18:21], v[188:191], v[236:239], 0
	v_mfma_f32_16x16x32_bf16 v[10:13], v[180:183], v[244:247], 0
	v_mfma_f32_16x16x32_bf16 v[2:5], v[188:191], v[244:247], 0
	v_mfma_f32_16x16x32_bf16 v[58:61], v[184:187], v[200:203], v[58:61]
	v_mfma_f32_16x16x32_bf16 v[50:53], v[192:195], v[200:203], v[50:53]
	v_mfma_f32_16x16x32_bf16 v[42:45], v[184:187], v[220:223], v[42:45]
	v_mfma_f32_16x16x32_bf16 v[34:37], v[192:195], v[220:223], v[34:37]
	v_mfma_f32_16x16x32_bf16 v[26:29], v[184:187], v[240:243], v[26:29]
	v_mfma_f32_16x16x32_bf16 v[18:21], v[192:195], v[240:243], v[18:21]
	v_mfma_f32_16x16x32_bf16 v[10:13], v[184:187], v[248:251], v[10:13]
	v_mfma_f32_16x16x32_bf16 v[2:5], v[192:195], v[248:251], v[2:5]
	s_barrier
	s_add_i32 s57, 0, 0x18000
	v_add_u32_e32 v164, s57, v155
	s_add_i32 s58, 0, 0x1c000
	ds_read_b128 v[142:145], v164
	ds_read_b128 v[168:171], v164 offset:1024
	ds_read_b128 v[172:175], v164 offset:2048
	ds_read_b128 v[176:179], v164 offset:3072
	v_add_u32_e32 v164, s58, v155
	ds_read_b128 v[180:183], v164
	ds_read_b128 v[184:187], v164 offset:1024
	ds_read_b128 v[188:191], v164 offset:2048
	ds_read_b128 v[192:195], v164 offset:3072
	s_add_u32 s36, s36, 0x40000
	s_addc_u32 s37, s37, 0
	s_mov_b32 m0, s50
	v_lshl_add_u64 v[252:253], s[36:37], 0, v[136:137]
	ds_read_b128 v[196:199], v157 offset:32768
	ds_read_b128 v[200:203], v157 offset:33792
	ds_read_b128 v[204:207], v157 offset:34816
	ds_read_b128 v[220:223], v157 offset:35840
	ds_read_b128 v[236:239], v157 offset:36864
	ds_read_b128 v[240:243], v157 offset:37888
	ds_read_b128 v[244:247], v157 offset:38912
	ds_read_b128 v[248:251], v157 offset:39936
	global_load_lds_dwordx4 v[252:253], off
	s_mov_b32 m0, s51
	v_lshl_add_u64 v[252:253], s[36:37], 0, v[132:133]
	global_load_lds_dwordx4 v[252:253], off
	s_branch .Lpadj_10
	s_nop 0
	s_nop 0
	s_nop 0
	s_nop 0
	s_nop 0
	s_nop 0
	s_nop 0
	s_nop 0
.Lpadj_10:
	s_waitcnt vmcnt(8)
	s_waitcnt lgkmcnt(0)
	s_barrier
	v_mfma_f32_16x16x32_bf16 v[126:129], v[142:145], v[196:199], v[126:129]
	v_mfma_f32_16x16x32_bf16 v[118:121], v[172:175], v[196:199], v[118:121]
	v_mfma_f32_16x16x32_bf16 v[110:113], v[142:145], v[204:207], v[110:113]
	v_mfma_f32_16x16x32_bf16 v[102:105], v[172:175], v[204:207], v[102:105]
	v_mfma_f32_16x16x32_bf16 v[94:97], v[142:145], v[236:239], v[94:97]
	v_mfma_f32_16x16x32_bf16 v[86:89], v[172:175], v[236:239], v[86:89]
	v_mfma_f32_16x16x32_bf16 v[78:81], v[142:145], v[244:247], v[78:81]
	v_mfma_f32_16x16x32_bf16 v[70:73], v[172:175], v[244:247], v[70:73]
	v_mfma_f32_16x16x32_bf16 v[126:129], v[168:171], v[200:203], v[126:129]
	v_mfma_f32_16x16x32_bf16 v[118:121], v[176:179], v[200:203], v[118:121]
	v_mfma_f32_16x16x32_bf16 v[110:113], v[168:171], v[220:223], v[110:113]
	v_mfma_f32_16x16x32_bf16 v[102:105], v[176:179], v[220:223], v[102:105]
	v_mfma_f32_16x16x32_bf16 v[94:97], v[168:171], v[240:243], v[94:97]
	v_mfma_f32_16x16x32_bf16 v[86:89], v[176:179], v[240:243], v[86:89]
	v_mfma_f32_16x16x32_bf16 v[78:81], v[168:171], v[248:251], v[78:81]
	v_mfma_f32_16x16x32_bf16 v[70:73], v[176:179], v[248:251], v[70:73]
	v_mfma_f32_16x16x32_bf16 v[122:125], v[180:183], v[196:199], v[122:125]
	v_mfma_f32_16x16x32_bf16 v[114:117], v[188:191], v[196:199], v[114:117]
	v_mfma_f32_16x16x32_bf16 v[106:109], v[180:183], v[204:207], v[106:109]
	v_mfma_f32_16x16x32_bf16 v[98:101], v[188:191], v[204:207], v[98:101]
	v_mfma_f32_16x16x32_bf16 v[90:93], v[180:183], v[236:239], v[90:93]
	v_mfma_f32_16x16x32_bf16 v[82:85], v[188:191], v[236:239], v[82:85]
	v_mfma_f32_16x16x32_bf16 v[74:77], v[180:183], v[244:247], v[74:77]
	v_mfma_f32_16x16x32_bf16 v[66:69], v[188:191], v[244:247], v[66:69]
	v_mfma_f32_16x16x32_bf16 v[122:125], v[184:187], v[200:203], v[122:125]
	v_mfma_f32_16x16x32_bf16 v[114:117], v[192:195], v[200:203], v[114:117]
	v_mfma_f32_16x16x32_bf16 v[106:109], v[184:187], v[220:223], v[106:109]
	v_mfma_f32_16x16x32_bf16 v[98:101], v[192:195], v[220:223], v[98:101]
	v_mfma_f32_16x16x32_bf16 v[90:93], v[184:187], v[240:243], v[90:93]
	v_mfma_f32_16x16x32_bf16 v[82:85], v[192:195], v[240:243], v[82:85]
	v_mfma_f32_16x16x32_bf16 v[74:77], v[184:187], v[248:251], v[74:77]
	v_mfma_f32_16x16x32_bf16 v[66:69], v[192:195], v[248:251], v[66:69]
	s_barrier
	s_add_i32 s36, s57, s44
	v_lshl_add_u64 v[146:147], v[146:147], 0, s[96:97]
	s_mov_b32 m0, s36
	ds_read_b128 v[196:199], v157 offset:49152
	ds_read_b128 v[200:203], v157 offset:50176
	ds_read_b128 v[204:207], v157 offset:51200
	ds_read_b128 v[220:223], v157 offset:52224
	ds_read_b128 v[236:239], v157 offset:53248
	ds_read_b128 v[240:243], v157 offset:54272
	ds_read_b128 v[244:247], v157 offset:55296
	ds_read_b128 v[248:251], v157 offset:56320
	global_load_lds_dwordx4 v[146:147], off
	s_add_i32 m0, s36, 0x2000
	s_add_u32 s34, s34, 0x40080
	v_lshl_add_u64 v[146:147], v[208:209], 0, s[96:97]
	s_addc_u32 s35, s35, 0
	s_add_i32 s36, s58, s44
	global_load_lds_dwordx4 v[146:147], off
	s_mov_b32 m0, s36
	v_lshl_add_u64 v[146:147], s[34:35], 0, v[134:135]
	global_load_lds_dwordx4 v[146:147], off
	s_add_i32 m0, s36, 0x2000
	v_lshl_add_u64 v[146:147], s[34:35], 0, v[130:131]
	global_load_lds_dwordx4 v[146:147], off
	s_mov_b32 m0, s52
	v_lshl_add_u64 v[146:147], v[224:225], 0, s[96:97]
	global_load_lds_dwordx4 v[146:147], off
	s_mov_b32 m0, s53
	v_lshl_add_u64 v[146:147], v[230:231], 0, s[96:97]
	global_load_lds_dwordx4 v[146:147], off
	s_branch .Lpadj_11
	s_nop 0
	s_nop 0
	s_nop 0
	s_nop 0
	s_nop 0
	s_nop 0
.Lpadj_11:
	s_waitcnt vmcnt(8)
	s_waitcnt lgkmcnt(0)
	s_barrier
	v_mfma_f32_16x16x32_bf16 v[62:65], v[142:145], v[196:199], v[62:65]
	v_mfma_f32_16x16x32_bf16 v[54:57], v[172:175], v[196:199], v[54:57]
	v_mfma_f32_16x16x32_bf16 v[46:49], v[142:145], v[204:207], v[46:49]
	v_mfma_f32_16x16x32_bf16 v[38:41], v[172:175], v[204:207], v[38:41]
	v_mfma_f32_16x16x32_bf16 v[30:33], v[142:145], v[236:239], v[30:33]
	v_mfma_f32_16x16x32_bf16 v[22:25], v[172:175], v[236:239], v[22:25]
	v_mfma_f32_16x16x32_bf16 v[14:17], v[142:145], v[244:247], v[14:17]
	v_mfma_f32_16x16x32_bf16 v[6:9], v[172:175], v[244:247], v[6:9]
	v_mfma_f32_16x16x32_bf16 v[62:65], v[168:171], v[200:203], v[62:65]
	v_mfma_f32_16x16x32_bf16 v[54:57], v[176:179], v[200:203], v[54:57]
	v_mfma_f32_16x16x32_bf16 v[46:49], v[168:171], v[220:223], v[46:49]
	v_mfma_f32_16x16x32_bf16 v[38:41], v[176:179], v[220:223], v[38:41]
	v_mfma_f32_16x16x32_bf16 v[30:33], v[168:171], v[240:243], v[30:33]
	v_mfma_f32_16x16x32_bf16 v[22:25], v[176:179], v[240:243], v[22:25]
	v_mfma_f32_16x16x32_bf16 v[14:17], v[168:171], v[248:251], v[14:17]
	v_mfma_f32_16x16x32_bf16 v[6:9], v[176:179], v[248:251], v[6:9]
	v_mfma_f32_16x16x32_bf16 v[58:61], v[180:183], v[196:199], v[58:61]
	v_mfma_f32_16x16x32_bf16 v[50:53], v[188:191], v[196:199], v[50:53]
	v_mfma_f32_16x16x32_bf16 v[42:45], v[180:183], v[204:207], v[42:45]
	v_mfma_f32_16x16x32_bf16 v[34:37], v[188:191], v[204:207], v[34:37]
	v_mfma_f32_16x16x32_bf16 v[26:29], v[180:183], v[236:239], v[26:29]
	v_mfma_f32_16x16x32_bf16 v[18:21], v[188:191], v[236:239], v[18:21]
	v_mfma_f32_16x16x32_bf16 v[10:13], v[180:183], v[244:247], v[10:13]
	v_mfma_f32_16x16x32_bf16 v[2:5], v[188:191], v[244:247], v[2:5]
	v_mfma_f32_16x16x32_bf16 v[58:61], v[184:187], v[200:203], v[58:61]
	v_mfma_f32_16x16x32_bf16 v[50:53], v[192:195], v[200:203], v[50:53]
	v_mfma_f32_16x16x32_bf16 v[42:45], v[184:187], v[220:223], v[42:45]
	v_mfma_f32_16x16x32_bf16 v[34:37], v[192:195], v[220:223], v[34:37]
	v_mfma_f32_16x16x32_bf16 v[26:29], v[184:187], v[240:243], v[26:29]
	v_mfma_f32_16x16x32_bf16 v[18:21], v[192:195], v[240:243], v[18:21]
	v_mfma_f32_16x16x32_bf16 v[10:13], v[184:187], v[248:251], v[10:13]
	v_mfma_f32_16x16x32_bf16 v[2:5], v[192:195], v[248:251], v[2:5]
	s_barrier
	s_add_i32 s56, s56, 2
	s_add_u32 s41, s41, 0x100
	s_addc_u32 s43, s43, 0
	s_add_u32 s30, s30, 0x100
	s_addc_u32 s31, s31, 0
	s_cmp_gt_u32 s56, 13
.LBB0_363:
	s_add_u32 s34, s30, 0xfffc0080
	s_addc_u32 s35, s31, -1
	s_add_i32 s57, 0, 0x10000
	s_cmp_eq_u32 s56, 12
	s_cselect_b32 s37, s23, s35
	s_cselect_b32 s36, s39, s34
	v_add_u32_e32 v146, s57, v155
	s_cselect_b32 s35, s21, s43
	s_cselect_b32 s34, s40, s41
	s_add_i32 s60, 0, 0x14000
	ds_read_b128 v[142:145], v146
	ds_read_b128 v[168:171], v146 offset:1024
	ds_read_b128 v[172:175], v146 offset:2048
	ds_read_b128 v[176:179], v146 offset:3072
	v_add_u32_e32 v146, s60, v155
	ds_read_b128 v[180:183], v146
	ds_read_b128 v[184:187], v146 offset:1024
	ds_read_b128 v[188:191], v146 offset:2048
	ds_read_b128 v[192:195], v146 offset:3072
	v_lshl_add_u64 v[146:147], s[30:31], 0, v[140:141]
	s_add_i32 m0, s48, 0xc000
	ds_read_b128 v[196:199], v157
	ds_read_b128 v[200:203], v157 offset:1024
	ds_read_b128 v[204:207], v157 offset:2048
	ds_read_b128 v[220:223], v157 offset:3072
	ds_read_b128 v[236:239], v157 offset:4096
	ds_read_b128 v[240:243], v157 offset:5120
	ds_read_b128 v[244:247], v157 offset:6144
	ds_read_b128 v[248:251], v157 offset:7168
	global_load_lds_dwordx4 v[146:147], off
	s_add_i32 m0, s48, 0xe000
	v_lshl_add_u64 v[146:147], s[30:31], 0, v[138:139]
	global_load_lds_dwordx4 v[146:147], off
	s_branch .Lpadj_12
	s_nop 0
	s_nop 0
	s_nop 0
	s_nop 0
	s_nop 0
	s_nop 0
	s_nop 0
	s_nop 0
	s_nop 0
.Lpadj_12:
	s_waitcnt vmcnt(8)
	s_waitcnt lgkmcnt(0)
	s_barrier
	v_mfma_f32_16x16x32_bf16 v[126:129], v[142:145], v[196:199], v[126:129]
	v_mfma_f32_16x16x32_bf16 v[118:121], v[172:175], v[196:199], v[118:121]
	v_mfma_f32_16x16x32_bf16 v[110:113], v[142:145], v[204:207], v[110:113]
	v_mfma_f32_16x16x32_bf16 v[102:105], v[172:175], v[204:207], v[102:105]
	v_mfma_f32_16x16x32_bf16 v[94:97], v[142:145], v[236:239], v[94:97]
	v_mfma_f32_16x16x32_bf16 v[86:89], v[172:175], v[236:239], v[86:89]
	v_mfma_f32_16x16x32_bf16 v[78:81], v[142:145], v[244:247], v[78:81]
	v_mfma_f32_16x16x32_bf16 v[70:73], v[172:175], v[244:247], v[70:73]
	v_mfma_f32_16x16x32_bf16 v[126:129], v[168:171], v[200:203], v[126:129]
	v_mfma_f32_16x16x32_bf16 v[118:121], v[176:179], v[200:203], v[118:121]
	v_mfma_f32_16x16x32_bf16 v[110:113], v[168:171], v[220:223], v[110:113]
	v_mfma_f32_16x16x32_bf16 v[102:105], v[176:179], v[220:223], v[102:105]
	v_mfma_f32_16x16x32_bf16 v[94:97], v[168:171], v[240:243], v[94:97]
	v_mfma_f32_16x16x32_bf16 v[86:89], v[176:179], v[240:243], v[86:89]
	v_mfma_f32_16x16x32_bf16 v[78:81], v[168:171], v[248:251], v[78:81]
	v_mfma_f32_16x16x32_bf16 v[70:73], v[176:179], v[248:251], v[70:73]
	v_mfma_f32_16x16x32_bf16 v[122:125], v[180:183], v[196:199], v[122:125]
	v_mfma_f32_16x16x32_bf16 v[114:117], v[188:191], v[196:199], v[114:117]
	v_mfma_f32_16x16x32_bf16 v[106:109], v[180:183], v[204:207], v[106:109]
	v_mfma_f32_16x16x32_bf16 v[98:101], v[188:191], v[204:207], v[98:101]
	v_mfma_f32_16x16x32_bf16 v[90:93], v[180:183], v[236:239], v[90:93]
	v_mfma_f32_16x16x32_bf16 v[82:85], v[188:191], v[236:239], v[82:85]
	v_mfma_f32_16x16x32_bf16 v[74:77], v[180:183], v[244:247], v[74:77]
	v_mfma_f32_16x16x32_bf16 v[66:69], v[188:191], v[244:247], v[66:69]
	v_mfma_f32_16x16x32_bf16 v[122:125], v[184:187], v[200:203], v[122:125]
	v_mfma_f32_16x16x32_bf16 v[114:117], v[192:195], v[200:203], v[114:117]
	v_mfma_f32_16x16x32_bf16 v[106:109], v[184:187], v[220:223], v[106:109]
	v_mfma_f32_16x16x32_bf16 v[98:101], v[192:195], v[220:223], v[98:101]
	v_mfma_f32_16x16x32_bf16 v[90:93], v[184:187], v[240:243], v[90:93]
	v_mfma_f32_16x16x32_bf16 v[82:85], v[192:195], v[240:243], v[82:85]
	v_mfma_f32_16x16x32_bf16 v[74:77], v[184:187], v[248:251], v[74:77]
	v_mfma_f32_16x16x32_bf16 v[66:69], v[192:195], v[248:251], v[66:69]
	s_barrier
	s_add_i32 s57, s57, s44
	v_lshl_add_u64 v[146:147], s[34:35], 0, v[134:135]
	s_mov_b32 m0, s57
	ds_read_b128 v[196:199], v157 offset:16384
	ds_read_b128 v[200:203], v157 offset:17408
	ds_read_b128 v[204:207], v157 offset:18432
	ds_read_b128 v[220:223], v157 offset:19456
	ds_read_b128 v[236:239], v157 offset:20480
	ds_read_b128 v[240:243], v157 offset:21504
	ds_read_b128 v[244:247], v157 offset:22528
	ds_read_b128 v[248:251], v157 offset:23552
	global_load_lds_dwordx4 v[146:147], off
	s_add_i32 m0, s57, 0x2000
	s_add_u32 s58, s34, 0x40000
	v_lshl_add_u64 v[208:209], s[34:35], 0, v[130:131]
	s_addc_u32 s59, s35, 0
	s_add_i32 s57, s60, s44
	global_load_lds_dwordx4 v[208:209], off
	v_lshl_add_u64 v[224:225], s[58:59], 0, v[134:135]
	s_mov_b32 m0, s57
	v_lshl_add_u64 v[230:231], s[36:37], 0, v[132:133]
	global_load_lds_dwordx4 v[224:225], off
	s_add_i32 m0, s57, 0x2000
	v_lshl_add_u64 v[224:225], s[58:59], 0, v[130:131]
	global_load_lds_dwordx4 v[224:225], off
	s_mov_b32 m0, s48
	v_lshl_add_u64 v[224:225], s[36:37], 0, v[136:137]
	global_load_lds_dwordx4 v[224:225], off
	s_mov_b32 m0, s49
	s_nop 0
	global_load_lds_dwordx4 v[230:231], off
	s_branch .Lpadj_13
	s_nop 0
	s_nop 0
	s_nop 0
	s_nop 0
	s_nop 0
.Lpadj_13:
	s_waitcnt vmcnt(8)
	s_waitcnt lgkmcnt(0)
	s_barrier
	v_mfma_f32_16x16x32_bf16 v[62:65], v[142:145], v[196:199], v[62:65]
	v_mfma_f32_16x16x32_bf16 v[54:57], v[172:175], v[196:199], v[54:57]
	v_mfma_f32_16x16x32_bf16 v[46:49], v[142:145], v[204:207], v[46:49]
	v_mfma_f32_16x16x32_bf16 v[38:41], v[172:175], v[204:207], v[38:41]
	v_mfma_f32_16x16x32_bf16 v[30:33], v[142:145], v[236:239], v[30:33]
	v_mfma_f32_16x16x32_bf16 v[22:25], v[172:175], v[236:239], v[22:25]
	v_mfma_f32_16x16x32_bf16 v[14:17], v[142:145], v[244:247], v[14:17]
	v_mfma_f32_16x16x32_bf16 v[6:9], v[172:175], v[244:247], v[6:9]
	v_mfma_f32_16x16x32_bf16 v[62:65], v[168:171], v[200:203], v[62:65]
	v_mfma_f32_16x16x32_bf16 v[54:57], v[176:179], v[200:203], v[54:57]
	v_mfma_f32_16x16x32_bf16 v[46:49], v[168:171], v[220:223], v[46:49]
	v_mfma_f32_16x16x32_bf16 v[38:41], v[176:179], v[220:223], v[38:41]
	v_mfma_f32_16x16x32_bf16 v[30:33], v[168:171], v[240:243], v[30:33]
	v_mfma_f32_16x16x32_bf16 v[22:25], v[176:179], v[240:243], v[22:25]
	v_mfma_f32_16x16x32_bf16 v[14:17], v[168:171], v[248:251], v[14:17]
	v_mfma_f32_16x16x32_bf16 v[6:9], v[176:179], v[248:251], v[6:9]
	v_mfma_f32_16x16x32_bf16 v[58:61], v[180:183], v[196:199], v[58:61]
	v_mfma_f32_16x16x32_bf16 v[50:53], v[188:191], v[196:199], v[50:53]
	v_mfma_f32_16x16x32_bf16 v[42:45], v[180:183], v[204:207], v[42:45]
	v_mfma_f32_16x16x32_bf16 v[34:37], v[188:191], v[204:207], v[34:37]
	v_mfma_f32_16x16x32_bf16 v[26:29], v[180:183], v[236:239], v[26:29]
	v_mfma_f32_16x16x32_bf16 v[18:21], v[188:191], v[236:239], v[18:21]
	v_mfma_f32_16x16x32_bf16 v[10:13], v[180:183], v[244:247], v[10:13]
	v_mfma_f32_16x16x32_bf16 v[2:5], v[188:191], v[244:247], v[2:5]
	v_mfma_f32_16x16x32_bf16 v[58:61], v[184:187], v[200:203], v[58:61]
	v_mfma_f32_16x16x32_bf16 v[50:53], v[192:195], v[200:203], v[50:53]
	v_mfma_f32_16x16x32_bf16 v[42:45], v[184:187], v[220:223], v[42:45]
	v_mfma_f32_16x16x32_bf16 v[34:37], v[192:195], v[220:223], v[34:37]
	v_mfma_f32_16x16x32_bf16 v[26:29], v[184:187], v[240:243], v[26:29]
	v_mfma_f32_16x16x32_bf16 v[18:21], v[192:195], v[240:243], v[18:21]
	v_mfma_f32_16x16x32_bf16 v[10:13], v[184:187], v[248:251], v[10:13]
	v_mfma_f32_16x16x32_bf16 v[2:5], v[192:195], v[248:251], v[2:5]
	s_barrier
	s_add_i32 s57, 0, 0x18000
	v_add_u32_e32 v164, s57, v155
	s_add_i32 s58, 0, 0x1c000
	ds_read_b128 v[142:145], v164
	ds_read_b128 v[168:171], v164 offset:1024
	ds_read_b128 v[172:175], v164 offset:2048
	ds_read_b128 v[176:179], v164 offset:3072
	v_add_u32_e32 v164, s58, v155
	ds_read_b128 v[180:183], v164
	ds_read_b128 v[184:187], v164 offset:1024
	ds_read_b128 v[188:191], v164 offset:2048
	ds_read_b128 v[192:195], v164 offset:3072
	s_add_u32 s36, s36, 0x40000
	s_addc_u32 s37, s37, 0
	s_mov_b32 m0, s50
	v_lshl_add_u64 v[252:253], s[36:37], 0, v[136:137]
	ds_read_b128 v[196:199], v157 offset:32768
	ds_read_b128 v[200:203], v157 offset:33792
	ds_read_b128 v[204:207], v157 offset:34816
	ds_read_b128 v[220:223], v157 offset:35840
	ds_read_b128 v[236:239], v157 offset:36864
	ds_read_b128 v[240:243], v157 offset:37888
	ds_read_b128 v[244:247], v157 offset:38912
	ds_read_b128 v[248:251], v157 offset:39936
	global_load_lds_dwordx4 v[252:253], off
	s_mov_b32 m0, s51
	v_lshl_add_u64 v[252:253], s[36:37], 0, v[132:133]
	global_load_lds_dwordx4 v[252:253], off
	s_branch .Lpadj_14
	s_nop 0
	s_nop 0
	s_nop 0
	s_nop 0
	s_nop 0
	s_nop 0
	s_nop 0
	s_nop 0

.Lpadj_15:
	s_waitcnt vmcnt(8)
	s_waitcnt lgkmcnt(0)
	s_barrier
	v_mfma_f32_16x16x32_bf16 v[62:65], v[142:145], v[196:199], v[62:65]
	v_mfma_f32_16x16x32_bf16 v[54:57], v[172:175], v[196:199], v[54:57]
	v_mfma_f32_16x16x32_bf16 v[46:49], v[142:145], v[204:207], v[46:49]
	v_mfma_f32_16x16x32_bf16 v[38:41], v[172:175], v[204:207], v[38:41]
	v_mfma_f32_16x16x32_bf16 v[30:33], v[142:145], v[236:239], v[30:33]
	v_mfma_f32_16x16x32_bf16 v[22:25], v[172:175], v[236:239], v[22:25]
	v_mfma_f32_16x16x32_bf16 v[14:17], v[142:145], v[244:247], v[14:17]
	v_mfma_f32_16x16x32_bf16 v[6:9], v[172:175], v[244:247], v[6:9]
	v_mfma_f32_16x16x32_bf16 v[62:65], v[168:171], v[200:203], v[62:65]
	v_mfma_f32_16x16x32_bf16 v[54:57], v[176:179], v[200:203], v[54:57]
	v_mfma_f32_16x16x32_bf16 v[46:49], v[168:171], v[220:223], v[46:49]
	v_mfma_f32_16x16x32_bf16 v[38:41], v[176:179], v[220:223], v[38:41]
	v_mfma_f32_16x16x32_bf16 v[30:33], v[168:171], v[240:243], v[30:33]
	v_mfma_f32_16x16x32_bf16 v[22:25], v[176:179], v[240:243], v[22:25]
	v_mfma_f32_16x16x32_bf16 v[14:17], v[168:171], v[248:251], v[14:17]
	v_mfma_f32_16x16x32_bf16 v[6:9], v[176:179], v[248:251], v[6:9]
	v_mfma_f32_16x16x32_bf16 v[58:61], v[180:183], v[196:199], v[58:61]
	v_mfma_f32_16x16x32_bf16 v[50:53], v[188:191], v[196:199], v[50:53]
	v_mfma_f32_16x16x32_bf16 v[42:45], v[180:183], v[204:207], v[42:45]
	v_mfma_f32_16x16x32_bf16 v[34:37], v[188:191], v[204:207], v[34:37]
	v_mfma_f32_16x16x32_bf16 v[26:29], v[180:183], v[236:239], v[26:29]
	v_mfma_f32_16x16x32_bf16 v[18:21], v[188:191], v[236:239], v[18:21]
	v_mfma_f32_16x16x32_bf16 v[10:13], v[180:183], v[244:247], v[10:13]
	v_mfma_f32_16x16x32_bf16 v[2:5], v[188:191], v[244:247], v[2:5]
	v_mfma_f32_16x16x32_bf16 v[58:61], v[184:187], v[200:203], v[58:61]
	v_mfma_f32_16x16x32_bf16 v[50:53], v[192:195], v[200:203], v[50:53]
	v_mfma_f32_16x16x32_bf16 v[42:45], v[184:187], v[220:223], v[42:45]
	v_mfma_f32_16x16x32_bf16 v[34:37], v[192:195], v[220:223], v[34:37]
	v_mfma_f32_16x16x32_bf16 v[26:29], v[184:187], v[240:243], v[26:29]
	v_mfma_f32_16x16x32_bf16 v[18:21], v[192:195], v[240:243], v[18:21]
	v_mfma_f32_16x16x32_bf16 v[10:13], v[184:187], v[248:251], v[10:13]
	v_mfma_f32_16x16x32_bf16 v[2:5], v[192:195], v[248:251], v[2:5]
	s_barrier
	s_add_i32 s56, s56, 2
	s_add_u32 s41, s41, 0x100
	s_addc_u32 s43, s43, 0
	s_add_u32 s30, s30, 0x100
	s_addc_u32 s31, s31, 0
	s_cmp_gt_u32 s56, 13
	s_cbranch_scc0 .LBB0_363
	s_and_b64 vcc, exec, s[16:17]
	s_cbranch_vccz .LBB0_366
	s_barrier

.LBB0_476:
	s_add_i32 s63, s31, 2
	s_add_u32 s38, s28, s36
	s_addc_u32 s39, s29, s37
	s_add_u32 s64, s26, s36
	s_addc_u32 s65, s27, s37
	s_add_i32 s66, 0, 0x10000
	s_cmp_eq_u32 s59, s31
	s_cselect_b32 s39, s9, s39
	s_cselect_b32 s38, s8, s38
	s_cselect_b32 s65, s35, s65
	s_cselect_b32 s64, s34, s64
	s_add_i32 s31, 0, 0x14000
	v_add_u32_e32 v160, s66, v146
	v_add_u32_e32 v176, s31, v146
	ds_read_b128 v[148:151], v160
	ds_read_b128 v[152:155], v160 offset:1024
	ds_read_b128 v[156:159], v160 offset:2048
	ds_read_b128 v[160:163], v160 offset:3072
	ds_read_b128 v[164:167], v176
	ds_read_b128 v[168:171], v176 offset:1024
	ds_read_b128 v[172:175], v176 offset:2048
	ds_read_b128 v[176:179], v176 offset:3072
	v_lshl_add_u64 v[208:209], s[28:29], 0, v[142:143]
	s_add_i32 m0, s51, 0xc000
	ds_read_b128 v[180:183], v147
	ds_read_b128 v[184:187], v147 offset:1024
	ds_read_b128 v[188:191], v147 offset:2048
	ds_read_b128 v[192:195], v147 offset:3072
	ds_read_b128 v[196:199], v147 offset:4096
	ds_read_b128 v[200:203], v147 offset:5120
	ds_read_b128 v[204:207], v147 offset:6144
	ds_read_b128 v[220:223], v147 offset:7168
	global_load_lds_dwordx4 v[208:209], off
	s_add_i32 m0, s51, 0xe000
	v_lshl_add_u64 v[208:209], s[28:29], 0, v[144:145]
	global_load_lds_dwordx4 v[208:209], off
	s_branch .Lpadj_16
	s_nop 0
	s_nop 0
	s_nop 0
	s_nop 0
	s_nop 0
	s_nop 0
	s_nop 0
	s_nop 0
	s_nop 0
	s_nop 0
	s_nop 0
.Lpadj_16:
	s_waitcnt vmcnt(8)
	s_waitcnt lgkmcnt(0)
	s_barrier
	v_mfma_f32_16x16x32_bf16 v[126:129], v[148:151], v[180:183], v[126:129]
	v_mfma_f32_16x16x32_bf16 v[122:125], v[156:159], v[180:183], v[122:125]
	v_mfma_f32_16x16x32_bf16 v[110:113], v[148:151], v[188:191], v[110:113]
	v_mfma_f32_16x16x32_bf16 v[106:109], v[156:159], v[188:191], v[106:109]
	v_mfma_f32_16x16x32_bf16 v[94:97], v[148:151], v[196:199], v[94:97]
	v_mfma_f32_16x16x32_bf16 v[90:93], v[156:159], v[196:199], v[90:93]
	v_mfma_f32_16x16x32_bf16 v[78:81], v[148:151], v[204:207], v[78:81]
	v_mfma_f32_16x16x32_bf16 v[74:77], v[156:159], v[204:207], v[74:77]
	v_mfma_f32_16x16x32_bf16 v[126:129], v[152:155], v[184:187], v[126:129]
	v_mfma_f32_16x16x32_bf16 v[122:125], v[160:163], v[184:187], v[122:125]
	v_mfma_f32_16x16x32_bf16 v[110:113], v[152:155], v[192:195], v[110:113]
	v_mfma_f32_16x16x32_bf16 v[106:109], v[160:163], v[192:195], v[106:109]
	v_mfma_f32_16x16x32_bf16 v[94:97], v[152:155], v[200:203], v[94:97]
	v_mfma_f32_16x16x32_bf16 v[90:93], v[160:163], v[200:203], v[90:93]
	v_mfma_f32_16x16x32_bf16 v[78:81], v[152:155], v[220:223], v[78:81]
	v_mfma_f32_16x16x32_bf16 v[74:77], v[160:163], v[220:223], v[74:77]
	v_mfma_f32_16x16x32_bf16 v[118:121], v[164:167], v[180:183], v[118:121]
	v_mfma_f32_16x16x32_bf16 v[114:117], v[172:175], v[180:183], v[114:117]
	v_mfma_f32_16x16x32_bf16 v[102:105], v[164:167], v[188:191], v[102:105]
	v_mfma_f32_16x16x32_bf16 v[98:101], v[172:175], v[188:191], v[98:101]
	v_mfma_f32_16x16x32_bf16 v[86:89], v[164:167], v[196:199], v[86:89]
	v_mfma_f32_16x16x32_bf16 v[82:85], v[172:175], v[196:199], v[82:85]
	v_mfma_f32_16x16x32_bf16 v[70:73], v[164:167], v[204:207], v[70:73]
	v_mfma_f32_16x16x32_bf16 v[66:69], v[172:175], v[204:207], v[66:69]
	v_mfma_f32_16x16x32_bf16 v[118:121], v[168:171], v[184:187], v[118:121]
	v_mfma_f32_16x16x32_bf16 v[114:117], v[176:179], v[184:187], v[114:117]
	v_mfma_f32_16x16x32_bf16 v[102:105], v[168:171], v[192:195], v[102:105]
	v_mfma_f32_16x16x32_bf16 v[98:101], v[176:179], v[192:195], v[98:101]
	v_mfma_f32_16x16x32_bf16 v[86:89], v[168:171], v[200:203], v[86:89]
	v_mfma_f32_16x16x32_bf16 v[82:85], v[176:179], v[200:203], v[82:85]
	v_mfma_f32_16x16x32_bf16 v[70:73], v[168:171], v[220:223], v[70:73]
	v_mfma_f32_16x16x32_bf16 v[66:69], v[176:179], v[220:223], v[66:69]
	s_barrier
	s_add_i32 s66, s66, s47
	v_lshl_add_u64 v[208:209], s[64:65], 0, v[132:133]
	s_mov_b32 m0, s66
	ds_read_b128 v[180:183], v147 offset:16384
	ds_read_b128 v[184:187], v147 offset:17408
	ds_read_b128 v[188:191], v147 offset:18432
	ds_read_b128 v[192:195], v147 offset:19456
	ds_read_b128 v[196:199], v147 offset:20480
	ds_read_b128 v[200:203], v147 offset:21504
	ds_read_b128 v[204:207], v147 offset:22528
	ds_read_b128 v[220:223], v147 offset:23552
	global_load_lds_dwordx4 v[208:209], off
	s_add_i32 m0, s66, 0x2000
	v_lshl_add_u64 v[224:225], s[64:65], 0, v[136:137]
	s_add_u32 s64, s64, s45
	s_addc_u32 s65, s65, 0
	s_add_i32 s31, s31, s47
	global_load_lds_dwordx4 v[224:225], off
	v_lshl_add_u64 v[230:231], s[64:65], 0, v[132:133]
	s_mov_b32 m0, s31
	v_lshl_add_u64 v[236:237], s[64:65], 0, v[136:137]
	global_load_lds_dwordx4 v[230:231], off
	s_add_i32 m0, s31, 0x2000
	v_lshl_add_u64 v[238:239], s[38:39], 0, v[130:131]
	global_load_lds_dwordx4 v[236:237], off
	s_mov_b32 m0, s51
	v_lshl_add_u64 v[240:241], s[38:39], 0, v[134:135]
	global_load_lds_dwordx4 v[238:239], off
	s_mov_b32 m0, s52
	s_nop 0
	global_load_lds_dwordx4 v[240:241], off
	s_branch .Lpadj_17
	s_nop 0
	s_nop 0
	s_nop 0
	s_nop 0
	s_nop 0
	s_nop 0
.Lpadj_17:
	s_waitcnt vmcnt(8)
	s_waitcnt lgkmcnt(0)
	s_barrier
	v_mfma_f32_16x16x32_bf16 v[62:65], v[148:151], v[180:183], v[62:65]
	v_mfma_f32_16x16x32_bf16 v[58:61], v[156:159], v[180:183], v[58:61]
	v_mfma_f32_16x16x32_bf16 v[46:49], v[148:151], v[188:191], v[46:49]
	v_mfma_f32_16x16x32_bf16 v[42:45], v[156:159], v[188:191], v[42:45]
	v_mfma_f32_16x16x32_bf16 v[30:33], v[148:151], v[196:199], v[30:33]
	v_mfma_f32_16x16x32_bf16 v[26:29], v[156:159], v[196:199], v[26:29]
	v_mfma_f32_16x16x32_bf16 v[14:17], v[148:151], v[204:207], v[14:17]
	v_mfma_f32_16x16x32_bf16 v[10:13], v[156:159], v[204:207], v[10:13]
	v_mfma_f32_16x16x32_bf16 v[62:65], v[152:155], v[184:187], v[62:65]
	v_mfma_f32_16x16x32_bf16 v[58:61], v[160:163], v[184:187], v[58:61]
	v_mfma_f32_16x16x32_bf16 v[46:49], v[152:155], v[192:195], v[46:49]
	v_mfma_f32_16x16x32_bf16 v[42:45], v[160:163], v[192:195], v[42:45]
	v_mfma_f32_16x16x32_bf16 v[30:33], v[152:155], v[200:203], v[30:33]
	v_mfma_f32_16x16x32_bf16 v[26:29], v[160:163], v[200:203], v[26:29]
	v_mfma_f32_16x16x32_bf16 v[14:17], v[152:155], v[220:223], v[14:17]
	v_mfma_f32_16x16x32_bf16 v[10:13], v[160:163], v[220:223], v[10:13]
	v_mfma_f32_16x16x32_bf16 v[54:57], v[164:167], v[180:183], v[54:57]
	v_mfma_f32_16x16x32_bf16 v[50:53], v[172:175], v[180:183], v[50:53]
	v_mfma_f32_16x16x32_bf16 v[38:41], v[164:167], v[188:191], v[38:41]
	v_mfma_f32_16x16x32_bf16 v[34:37], v[172:175], v[188:191], v[34:37]
	v_mfma_f32_16x16x32_bf16 v[22:25], v[164:167], v[196:199], v[22:25]
	v_mfma_f32_16x16x32_bf16 v[18:21], v[172:175], v[196:199], v[18:21]
	v_mfma_f32_16x16x32_bf16 v[6:9], v[164:167], v[204:207], v[6:9]
	v_mfma_f32_16x16x32_bf16 v[2:5], v[172:175], v[204:207], v[2:5]
	v_mfma_f32_16x16x32_bf16 v[54:57], v[168:171], v[184:187], v[54:57]
	v_mfma_f32_16x16x32_bf16 v[50:53], v[176:179], v[184:187], v[50:53]
	v_mfma_f32_16x16x32_bf16 v[38:41], v[168:171], v[192:195], v[38:41]
	v_mfma_f32_16x16x32_bf16 v[34:37], v[176:179], v[192:195], v[34:37]
	v_mfma_f32_16x16x32_bf16 v[22:25], v[168:171], v[200:203], v[22:25]
	v_mfma_f32_16x16x32_bf16 v[18:21], v[176:179], v[200:203], v[18:21]
	v_mfma_f32_16x16x32_bf16 v[6:9], v[168:171], v[220:223], v[6:9]
	v_mfma_f32_16x16x32_bf16 v[2:5], v[176:179], v[220:223], v[2:5]
	s_barrier
	s_add_i32 s31, 0, 0x18000
	s_add_i32 s64, 0, 0x1c000
	v_add_u32_e32 v160, s31, v146
	v_add_u32_e32 v176, s64, v146
	ds_read_b128 v[148:151], v160
	ds_read_b128 v[152:155], v160 offset:1024
	ds_read_b128 v[156:159], v160 offset:2048
	ds_read_b128 v[160:163], v160 offset:3072
	ds_read_b128 v[164:167], v176
	ds_read_b128 v[168:171], v176 offset:1024
	ds_read_b128 v[172:175], v176 offset:2048
	ds_read_b128 v[176:179], v176 offset:3072
	s_add_u32 s38, s38, s45
	s_addc_u32 s39, s39, 0
	s_mov_b32 m0, s53
	v_lshl_add_u64 v[242:243], s[38:39], 0, v[130:131]
	ds_read_b128 v[180:183], v147 offset:32768
	ds_read_b128 v[184:187], v147 offset:33792
	ds_read_b128 v[188:191], v147 offset:34816
	ds_read_b128 v[192:195], v147 offset:35840
	ds_read_b128 v[196:199], v147 offset:36864
	ds_read_b128 v[200:203], v147 offset:37888
	ds_read_b128 v[204:207], v147 offset:38912
	ds_read_b128 v[220:223], v147 offset:39936
	global_load_lds_dwordx4 v[242:243], off
	s_mov_b32 m0, s54
	v_lshl_add_u64 v[242:243], s[38:39], 0, v[134:135]
	global_load_lds_dwordx4 v[242:243], off
	s_branch .Lpadj_18
	s_nop 0
	s_nop 0
	s_nop 0
	s_nop 0
	s_nop 0
	s_nop 0
	s_nop 0
	s_nop 0
	s_nop 0
.Lpadj_18:
	s_waitcnt vmcnt(8)
	s_waitcnt lgkmcnt(0)
	s_barrier
	v_mfma_f32_16x16x32_bf16 v[126:129], v[148:151], v[180:183], v[126:129]
	v_mfma_f32_16x16x32_bf16 v[122:125], v[156:159], v[180:183], v[122:125]
	v_mfma_f32_16x16x32_bf16 v[110:113], v[148:151], v[188:191], v[110:113]
	v_mfma_f32_16x16x32_bf16 v[106:109], v[156:159], v[188:191], v[106:109]
	v_mfma_f32_16x16x32_bf16 v[94:97], v[148:151], v[196:199], v[94:97]
	v_mfma_f32_16x16x32_bf16 v[90:93], v[156:159], v[196:199], v[90:93]
	v_mfma_f32_16x16x32_bf16 v[78:81], v[148:151], v[204:207], v[78:81]
	v_mfma_f32_16x16x32_bf16 v[74:77], v[156:159], v[204:207], v[74:77]
	v_mfma_f32_16x16x32_bf16 v[126:129], v[152:155], v[184:187], v[126:129]
	v_mfma_f32_16x16x32_bf16 v[122:125], v[160:163], v[184:187], v[122:125]
	v_mfma_f32_16x16x32_bf16 v[110:113], v[152:155], v[192:195], v[110:113]
	v_mfma_f32_16x16x32_bf16 v[106:109], v[160:163], v[192:195], v[106:109]
	v_mfma_f32_16x16x32_bf16 v[94:97], v[152:155], v[200:203], v[94:97]
	v_mfma_f32_16x16x32_bf16 v[90:93], v[160:163], v[200:203], v[90:93]
	v_mfma_f32_16x16x32_bf16 v[78:81], v[152:155], v[220:223], v[78:81]
	v_mfma_f32_16x16x32_bf16 v[74:77], v[160:163], v[220:223], v[74:77]
	v_mfma_f32_16x16x32_bf16 v[118:121], v[164:167], v[180:183], v[118:121]
	v_mfma_f32_16x16x32_bf16 v[114:117], v[172:175], v[180:183], v[114:117]
	v_mfma_f32_16x16x32_bf16 v[102:105], v[164:167], v[188:191], v[102:105]
	v_mfma_f32_16x16x32_bf16 v[98:101], v[172:175], v[188:191], v[98:101]
	v_mfma_f32_16x16x32_bf16 v[86:89], v[164:167], v[196:199], v[86:89]
	v_mfma_f32_16x16x32_bf16 v[82:85], v[172:175], v[196:199], v[82:85]
	v_mfma_f32_16x16x32_bf16 v[70:73], v[164:167], v[204:207], v[70:73]
	v_mfma_f32_16x16x32_bf16 v[66:69], v[172:175], v[204:207], v[66:69]
	v_mfma_f32_16x16x32_bf16 v[118:121], v[168:171], v[184:187], v[118:121]
	v_mfma_f32_16x16x32_bf16 v[114:117], v[176:179], v[184:187], v[114:117]
	v_mfma_f32_16x16x32_bf16 v[102:105], v[168:171], v[192:195], v[102:105]
	v_mfma_f32_16x16x32_bf16 v[98:101], v[176:179], v[192:195], v[98:101]
	v_mfma_f32_16x16x32_bf16 v[86:89], v[168:171], v[200:203], v[86:89]
	v_mfma_f32_16x16x32_bf16 v[82:85], v[176:179], v[200:203], v[82:85]
	v_mfma_f32_16x16x32_bf16 v[70:73], v[168:171], v[220:223], v[70:73]
	v_mfma_f32_16x16x32_bf16 v[66:69], v[176:179], v[220:223], v[66:69]
	s_barrier
	s_add_i32 s31, s31, s47
	v_lshl_add_u64 v[208:209], v[208:209], 0, s[96:97]
	s_mov_b32 m0, s31
	ds_read_b128 v[180:183], v147 offset:49152
	ds_read_b128 v[184:187], v147 offset:50176
	ds_read_b128 v[188:191], v147 offset:51200
	ds_read_b128 v[192:195], v147 offset:52224
	ds_read_b128 v[196:199], v147 offset:53248
	ds_read_b128 v[200:203], v147 offset:54272
	ds_read_b128 v[204:207], v147 offset:55296
	ds_read_b128 v[220:223], v147 offset:56320
	global_load_lds_dwordx4 v[208:209], off
	v_lshl_add_u64 v[208:209], v[224:225], 0, s[96:97]
	s_add_i32 m0, s31, 0x2000
	s_add_i32 s31, s64, s47
	global_load_lds_dwordx4 v[208:209], off
	s_mov_b32 m0, s31
	v_lshl_add_u64 v[208:209], v[230:231], 0, s[96:97]
	global_load_lds_dwordx4 v[208:209], off
	s_add_i32 m0, s31, 0x2000
	v_lshl_add_u64 v[208:209], v[236:237], 0, s[96:97]
	global_load_lds_dwordx4 v[208:209], off
	s_mov_b32 m0, s57
	v_lshl_add_u64 v[208:209], v[238:239], 0, s[96:97]
	global_load_lds_dwordx4 v[208:209], off
	s_mov_b32 m0, s58
	v_lshl_add_u64 v[208:209], v[240:241], 0, s[96:97]
	global_load_lds_dwordx4 v[208:209], off
	s_branch .Lpadj_19
	s_nop 0
	s_nop 0
	s_nop 0
	s_nop 0
	s_nop 0
	s_nop 0
	s_nop 0
	s_nop 0
	s_nop 0
.Lpadj_19:
	s_waitcnt vmcnt(8)
	s_waitcnt lgkmcnt(0)
	s_barrier
	v_mfma_f32_16x16x32_bf16 v[62:65], v[148:151], v[180:183], v[62:65]
	v_mfma_f32_16x16x32_bf16 v[58:61], v[156:159], v[180:183], v[58:61]
	v_mfma_f32_16x16x32_bf16 v[46:49], v[148:151], v[188:191], v[46:49]
	v_mfma_f32_16x16x32_bf16 v[42:45], v[156:159], v[188:191], v[42:45]
	v_mfma_f32_16x16x32_bf16 v[30:33], v[148:151], v[196:199], v[30:33]
	v_mfma_f32_16x16x32_bf16 v[26:29], v[156:159], v[196:199], v[26:29]
	v_mfma_f32_16x16x32_bf16 v[14:17], v[148:151], v[204:207], v[14:17]
	v_mfma_f32_16x16x32_bf16 v[10:13], v[156:159], v[204:207], v[10:13]
	v_mfma_f32_16x16x32_bf16 v[62:65], v[152:155], v[184:187], v[62:65]
	v_mfma_f32_16x16x32_bf16 v[58:61], v[160:163], v[184:187], v[58:61]
	v_mfma_f32_16x16x32_bf16 v[46:49], v[152:155], v[192:195], v[46:49]
	v_mfma_f32_16x16x32_bf16 v[42:45], v[160:163], v[192:195], v[42:45]
	v_mfma_f32_16x16x32_bf16 v[30:33], v[152:155], v[200:203], v[30:33]
	v_mfma_f32_16x16x32_bf16 v[26:29], v[160:163], v[200:203], v[26:29]
	v_mfma_f32_16x16x32_bf16 v[14:17], v[152:155], v[220:223], v[14:17]
	v_mfma_f32_16x16x32_bf16 v[10:13], v[160:163], v[220:223], v[10:13]
	v_mfma_f32_16x16x32_bf16 v[54:57], v[164:167], v[180:183], v[54:57]
	v_mfma_f32_16x16x32_bf16 v[50:53], v[172:175], v[180:183], v[50:53]
	v_mfma_f32_16x16x32_bf16 v[38:41], v[164:167], v[188:191], v[38:41]
	v_mfma_f32_16x16x32_bf16 v[34:37], v[172:175], v[188:191], v[34:37]
	v_mfma_f32_16x16x32_bf16 v[22:25], v[164:167], v[196:199], v[22:25]
	v_mfma_f32_16x16x32_bf16 v[18:21], v[172:175], v[196:199], v[18:21]
	v_mfma_f32_16x16x32_bf16 v[6:9], v[164:167], v[204:207], v[6:9]
	v_mfma_f32_16x16x32_bf16 v[2:5], v[172:175], v[204:207], v[2:5]
	v_mfma_f32_16x16x32_bf16 v[54:57], v[168:171], v[184:187], v[54:57]
	v_mfma_f32_16x16x32_bf16 v[50:53], v[176:179], v[184:187], v[50:53]
	v_mfma_f32_16x16x32_bf16 v[38:41], v[168:171], v[192:195], v[38:41]
	v_mfma_f32_16x16x32_bf16 v[34:37], v[176:179], v[192:195], v[34:37]
	v_mfma_f32_16x16x32_bf16 v[22:25], v[168:171], v[200:203], v[22:25]
	v_mfma_f32_16x16x32_bf16 v[18:21], v[176:179], v[200:203], v[18:21]
	v_mfma_f32_16x16x32_bf16 v[6:9], v[168:171], v[220:223], v[6:9]
	v_mfma_f32_16x16x32_bf16 v[2:5], v[176:179], v[220:223], v[2:5]
	s_barrier
	s_add_u32 s36, s36, 0x100
	s_addc_u32 s37, s37, 0
	v_lshl_add_u64 v[144:145], v[144:145], 0, s[2:3]
	v_lshl_add_u64 v[142:143], v[142:143], 0, s[2:3]
	s_cmp_ge_u32 s63, s56
	s_mov_b32 s31, s63
	s_cbranch_scc0 .LBB0_476
	s_and_b64 vcc, exec, s[6:7]
	s_cbranch_vccnz .LBB0_464
	v_mov_b32_e32 v2, 0
	s_mov_b32 s55, s61
	s_mov_b32 s50, s62
	s_mov_b64 s[26:27], s[34:35]
	s_mov_b64 s[28:29], s[8:9]
	s_mov_b32 s60, s30
	v_mov_b32_e32 v3, v2
	v_mov_b32_e32 v4, v2
	v_mov_b32_e32 v5, v2
	v_mov_b32_e32 v6, v2
	v_mov_b32_e32 v7, v2
	v_mov_b32_e32 v8, v2
	v_mov_b32_e32 v9, v2
	v_mov_b32_e32 v18, v2
	v_mov_b32_e32 v19, v2
	v_mov_b32_e32 v20, v2
	v_mov_b32_e32 v21, v2
	v_mov_b32_e32 v22, v2
	v_mov_b32_e32 v23, v2
	v_mov_b32_e32 v24, v2
	v_mov_b32_e32 v25, v2
	v_mov_b32_e32 v34, v2
	v_mov_b32_e32 v35, v2
	v_mov_b32_e32 v36, v2
	v_mov_b32_e32 v37, v2
	v_mov_b32_e32 v38, v2
	v_mov_b32_e32 v39, v2
	v_mov_b32_e32 v40, v2
	v_mov_b32_e32 v41, v2
	v_mov_b32_e32 v50, v2
	v_mov_b32_e32 v51, v2
	v_mov_b32_e32 v52, v2
	v_mov_b32_e32 v53, v2
	v_mov_b32_e32 v54, v2
	v_mov_b32_e32 v55, v2
	v_mov_b32_e32 v56, v2
	v_mov_b32_e32 v57, v2
	v_mov_b32_e32 v10, v2
	v_mov_b32_e32 v11, v2
	v_mov_b32_e32 v12, v2
	v_mov_b32_e32 v13, v2
	v_mov_b32_e32 v14, v2
	v_mov_b32_e32 v15, v2
	v_mov_b32_e32 v16, v2
	v_mov_b32_e32 v17, v2
	v_mov_b32_e32 v26, v2
	v_mov_b32_e32 v27, v2
	v_mov_b32_e32 v28, v2
	v_mov_b32_e32 v29, v2
	v_mov_b32_e32 v30, v2
	v_mov_b32_e32 v31, v2
	v_mov_b32_e32 v32, v2
	v_mov_b32_e32 v33, v2
	v_mov_b32_e32 v42, v2
	v_mov_b32_e32 v43, v2
	v_mov_b32_e32 v44, v2
	v_mov_b32_e32 v45, v2
	v_mov_b32_e32 v46, v2
	v_mov_b32_e32 v47, v2
	v_mov_b32_e32 v48, v2
	v_mov_b32_e32 v49, v2
	v_mov_b32_e32 v58, v2
	v_mov_b32_e32 v59, v2
	v_mov_b32_e32 v60, v2
	v_mov_b32_e32 v61, v2
	v_mov_b32_e32 v62, v2
	v_mov_b32_e32 v63, v2
	v_mov_b32_e32 v64, v2
	v_mov_b32_e32 v65, v2
	v_mov_b32_e32 v66, v2
	v_mov_b32_e32 v67, v2
	v_mov_b32_e32 v68, v2
	v_mov_b32_e32 v69, v2
	v_mov_b32_e32 v70, v2
	v_mov_b32_e32 v71, v2
	v_mov_b32_e32 v72, v2
	v_mov_b32_e32 v73, v2
	v_mov_b32_e32 v82, v2
	v_mov_b32_e32 v83, v2
	v_mov_b32_e32 v84, v2
	v_mov_b32_e32 v85, v2
	v_mov_b32_e32 v86, v2
	v_mov_b32_e32 v87, v2
	v_mov_b32_e32 v88, v2
	v_mov_b32_e32 v89, v2
	v_mov_b32_e32 v98, v2
	v_mov_b32_e32 v99, v2
	v_mov_b32_e32 v100, v2
	v_mov_b32_e32 v101, v2
	v_mov_b32_e32 v102, v2
	v_mov_b32_e32 v103, v2
	v_mov_b32_e32 v104, v2
	v_mov_b32_e32 v105, v2
	v_mov_b32_e32 v114, v2
	v_mov_b32_e32 v115, v2
	v_mov_b32_e32 v116, v2
	v_mov_b32_e32 v117, v2
	v_mov_b32_e32 v118, v2
	v_mov_b32_e32 v119, v2
	v_mov_b32_e32 v120, v2
	v_mov_b32_e32 v121, v2
	v_mov_b32_e32 v74, v2
	v_mov_b32_e32 v75, v2
	v_mov_b32_e32 v76, v2
	v_mov_b32_e32 v77, v2
	v_mov_b32_e32 v78, v2
	v_mov_b32_e32 v79, v2
	v_mov_b32_e32 v80, v2
	v_mov_b32_e32 v81, v2
	v_mov_b32_e32 v90, v2
	v_mov_b32_e32 v91, v2
	v_mov_b32_e32 v92, v2
	v_mov_b32_e32 v93, v2
	v_mov_b32_e32 v94, v2
	v_mov_b32_e32 v95, v2
	v_mov_b32_e32 v96, v2
	v_mov_b32_e32 v97, v2
	v_mov_b32_e32 v106, v2
	v_mov_b32_e32 v107, v2
	v_mov_b32_e32 v108, v2
	v_mov_b32_e32 v109, v2
	v_mov_b32_e32 v110, v2
	v_mov_b32_e32 v111, v2
	v_mov_b32_e32 v112, v2
	v_mov_b32_e32 v113, v2
	v_mov_b32_e32 v122, v2
	v_mov_b32_e32 v123, v2
	v_mov_b32_e32 v124, v2
	v_mov_b32_e32 v125, v2
	v_mov_b32_e32 v126, v2
	v_mov_b32_e32 v127, v2
	v_mov_b32_e32 v128, v2
	v_mov_b32_e32 v129, v2
	s_branch .LBB0_464

.LBB0_639:
	s_ashr_i32 s13, s12, 31
	s_lshl_b64 s[14:15], s[12:13], 19
	s_add_u32 s14, s80, s14
	s_addc_u32 s15, s81, s15
	s_and_b64 s[16:17], s[4:5], exec
	s_cselect_b32 s13, s15, s23
	s_cselect_b32 s19, s14, s22
	s_ashr_i32 s11, s10, 31
	s_lshl_b64 s[16:17], s[10:11], 19
	s_add_u32 s16, s26, s16
	s_addc_u32 s17, s27, s17
	s_and_b64 s[24:25], s[4:5], exec
	s_cselect_b32 s11, s17, s21
	s_cselect_b32 s41, s16, s20
	s_add_u32 s43, s20, 0x100
	s_addc_u32 s44, s21, 0
	s_add_u32 s20, s22, 0x40080
	s_addc_u32 s21, s23, 0
	s_mov_b32 s45, -2
	s_add_u32 s22, s20, 0xfffc0080
	s_addc_u32 s23, s21, -1
	s_add_i32 s46, 0, 0x10000
	s_cmp_eq_u32 s45, 12
	s_cselect_b32 s25, s13, s23
	s_cselect_b32 s24, s19, s22
	v_add_u32_e32 v150, s46, v159
	s_cselect_b32 s23, s11, s44
	s_cselect_b32 s22, s41, s43
	s_add_i32 s48, 0, 0x14000
	ds_read_b128 v[164:167], v150
	ds_read_b128 v[168:171], v150 offset:1024
	ds_read_b128 v[172:175], v150 offset:2048
	ds_read_b128 v[176:179], v150 offset:3072
	v_add_u32_e32 v150, s48, v159
	ds_read_b128 v[180:183], v150
	ds_read_b128 v[184:187], v150 offset:1024
	ds_read_b128 v[188:191], v150 offset:2048
	ds_read_b128 v[192:195], v150 offset:3072
	v_lshl_add_u64 v[150:151], s[20:21], 0, v[140:141]
	s_add_i32 m0, s30, 0xc000
	ds_read_b128 v[196:199], v162
	ds_read_b128 v[200:203], v162 offset:1024
	ds_read_b128 v[204:207], v162 offset:2048
	ds_read_b128 v[220:223], v162 offset:3072
	ds_read_b128 v[236:239], v162 offset:4096
	ds_read_b128 v[240:243], v162 offset:5120
	ds_read_b128 v[244:247], v162 offset:6144
	ds_read_b128 v[248:251], v162 offset:7168
	global_load_lds_dwordx4 v[150:151], off
	s_add_i32 m0, s30, 0xe000
	v_lshl_add_u64 v[150:151], s[20:21], 0, v[138:139]
	global_load_lds_dwordx4 v[150:151], off
	s_branch .Lpadj_20
	s_nop 0
	s_nop 0
	s_nop 0
	s_nop 0
	s_nop 0
	s_nop 0
	s_nop 0
	s_nop 0
	s_nop 0
.Lpadj_20:
	s_waitcnt vmcnt(8)
	s_waitcnt lgkmcnt(0)
	s_barrier
	v_mfma_f32_16x16x32_bf16 v[126:129], v[164:167], v[196:199], 0
	v_mfma_f32_16x16x32_bf16 v[122:125], v[172:175], v[196:199], 0
	v_mfma_f32_16x16x32_bf16 v[118:121], v[164:167], v[204:207], 0
	v_mfma_f32_16x16x32_bf16 v[114:117], v[172:175], v[204:207], 0
	v_mfma_f32_16x16x32_bf16 v[110:113], v[164:167], v[236:239], 0
	v_mfma_f32_16x16x32_bf16 v[106:109], v[172:175], v[236:239], 0
	v_mfma_f32_16x16x32_bf16 v[102:105], v[164:167], v[244:247], 0
	v_mfma_f32_16x16x32_bf16 v[98:101], v[172:175], v[244:247], 0
	v_mfma_f32_16x16x32_bf16 v[126:129], v[168:171], v[200:203], v[126:129]
	v_mfma_f32_16x16x32_bf16 v[122:125], v[176:179], v[200:203], v[122:125]
	v_mfma_f32_16x16x32_bf16 v[118:121], v[168:171], v[220:223], v[118:121]
	v_mfma_f32_16x16x32_bf16 v[114:117], v[176:179], v[220:223], v[114:117]
	v_mfma_f32_16x16x32_bf16 v[110:113], v[168:171], v[240:243], v[110:113]
	v_mfma_f32_16x16x32_bf16 v[106:109], v[176:179], v[240:243], v[106:109]
	v_mfma_f32_16x16x32_bf16 v[102:105], v[168:171], v[248:251], v[102:105]
	v_mfma_f32_16x16x32_bf16 v[98:101], v[176:179], v[248:251], v[98:101]
	v_mfma_f32_16x16x32_bf16 v[94:97], v[180:183], v[196:199], 0
	v_mfma_f32_16x16x32_bf16 v[90:93], v[188:191], v[196:199], 0
	v_mfma_f32_16x16x32_bf16 v[86:89], v[180:183], v[204:207], 0
	v_mfma_f32_16x16x32_bf16 v[82:85], v[188:191], v[204:207], 0
	v_mfma_f32_16x16x32_bf16 v[78:81], v[180:183], v[236:239], 0
	v_mfma_f32_16x16x32_bf16 v[74:77], v[188:191], v[236:239], 0
	v_mfma_f32_16x16x32_bf16 v[70:73], v[180:183], v[244:247], 0
	v_mfma_f32_16x16x32_bf16 v[66:69], v[188:191], v[244:247], 0
	v_mfma_f32_16x16x32_bf16 v[94:97], v[184:187], v[200:203], v[94:97]
	v_mfma_f32_16x16x32_bf16 v[90:93], v[192:195], v[200:203], v[90:93]
	v_mfma_f32_16x16x32_bf16 v[86:89], v[184:187], v[220:223], v[86:89]
	v_mfma_f32_16x16x32_bf16 v[82:85], v[192:195], v[220:223], v[82:85]
	v_mfma_f32_16x16x32_bf16 v[78:81], v[184:187], v[240:243], v[78:81]
	v_mfma_f32_16x16x32_bf16 v[74:77], v[192:195], v[240:243], v[74:77]
	v_mfma_f32_16x16x32_bf16 v[70:73], v[184:187], v[248:251], v[70:73]
	v_mfma_f32_16x16x32_bf16 v[66:69], v[192:195], v[248:251], v[66:69]
	s_barrier
	s_add_i32 s46, s46, s28
	v_lshl_add_u64 v[150:151], s[22:23], 0, v[134:135]
	s_mov_b32 m0, s46
	ds_read_b128 v[196:199], v162 offset:16384
	ds_read_b128 v[200:203], v162 offset:17408
	ds_read_b128 v[204:207], v162 offset:18432
	ds_read_b128 v[220:223], v162 offset:19456
	ds_read_b128 v[236:239], v162 offset:20480
	ds_read_b128 v[240:243], v162 offset:21504
	ds_read_b128 v[244:247], v162 offset:22528
	ds_read_b128 v[248:251], v162 offset:23552
	global_load_lds_dwordx4 v[150:151], off
	s_add_i32 m0, s46, 0x2000
	s_add_u32 s46, s22, 0x40000
	v_lshl_add_u64 v[208:209], s[22:23], 0, v[130:131]
	s_addc_u32 s47, s23, 0
	s_add_i32 s48, s48, s28
	global_load_lds_dwordx4 v[208:209], off
	v_lshl_add_u64 v[224:225], s[46:47], 0, v[134:135]
	s_mov_b32 m0, s48
	v_lshl_add_u64 v[252:253], s[24:25], 0, v[132:133]
	global_load_lds_dwordx4 v[224:225], off
	s_add_i32 m0, s48, 0x2000
	v_lshl_add_u64 v[224:225], s[46:47], 0, v[130:131]
	global_load_lds_dwordx4 v[224:225], off
	s_mov_b32 m0, s30
	v_lshl_add_u64 v[224:225], s[24:25], 0, v[136:137]
	global_load_lds_dwordx4 v[224:225], off
	s_mov_b32 m0, s31
	s_nop 0
	global_load_lds_dwordx4 v[252:253], off
	s_branch .Lpadj_21
	s_nop 0
	s_nop 0
	s_nop 0
	s_nop 0
	s_nop 0
.Lpadj_21:
	s_waitcnt vmcnt(8)
	s_waitcnt lgkmcnt(0)
	s_barrier
	v_mfma_f32_16x16x32_bf16 v[62:65], v[164:167], v[196:199], 0
	v_mfma_f32_16x16x32_bf16 v[58:61], v[172:175], v[196:199], 0
	v_mfma_f32_16x16x32_bf16 v[54:57], v[164:167], v[204:207], 0
	v_mfma_f32_16x16x32_bf16 v[50:53], v[172:175], v[204:207], 0
	v_mfma_f32_16x16x32_bf16 v[46:49], v[164:167], v[236:239], 0
	v_mfma_f32_16x16x32_bf16 v[42:45], v[172:175], v[236:239], 0
	v_mfma_f32_16x16x32_bf16 v[38:41], v[164:167], v[244:247], 0
	v_mfma_f32_16x16x32_bf16 v[34:37], v[172:175], v[244:247], 0
	v_mfma_f32_16x16x32_bf16 v[62:65], v[168:171], v[200:203], v[62:65]
	v_mfma_f32_16x16x32_bf16 v[58:61], v[176:179], v[200:203], v[58:61]
	v_mfma_f32_16x16x32_bf16 v[54:57], v[168:171], v[220:223], v[54:57]
	v_mfma_f32_16x16x32_bf16 v[50:53], v[176:179], v[220:223], v[50:53]
	v_mfma_f32_16x16x32_bf16 v[46:49], v[168:171], v[240:243], v[46:49]
	v_mfma_f32_16x16x32_bf16 v[42:45], v[176:179], v[240:243], v[42:45]
	v_mfma_f32_16x16x32_bf16 v[38:41], v[168:171], v[248:251], v[38:41]
	v_mfma_f32_16x16x32_bf16 v[34:37], v[176:179], v[248:251], v[34:37]
	v_mfma_f32_16x16x32_bf16 v[30:33], v[180:183], v[196:199], 0
	v_mfma_f32_16x16x32_bf16 v[26:29], v[188:191], v[196:199], 0
	v_mfma_f32_16x16x32_bf16 v[22:25], v[180:183], v[204:207], 0
	v_mfma_f32_16x16x32_bf16 v[18:21], v[188:191], v[204:207], 0
	v_mfma_f32_16x16x32_bf16 v[14:17], v[180:183], v[236:239], 0
	v_mfma_f32_16x16x32_bf16 v[10:13], v[188:191], v[236:239], 0
	v_mfma_f32_16x16x32_bf16 v[6:9], v[180:183], v[244:247], 0
	v_mfma_f32_16x16x32_bf16 v[2:5], v[188:191], v[244:247], 0
	v_mfma_f32_16x16x32_bf16 v[30:33], v[184:187], v[200:203], v[30:33]
	v_mfma_f32_16x16x32_bf16 v[26:29], v[192:195], v[200:203], v[26:29]
	v_mfma_f32_16x16x32_bf16 v[22:25], v[184:187], v[220:223], v[22:25]
	v_mfma_f32_16x16x32_bf16 v[18:21], v[192:195], v[220:223], v[18:21]
	v_mfma_f32_16x16x32_bf16 v[14:17], v[184:187], v[240:243], v[14:17]
	v_mfma_f32_16x16x32_bf16 v[10:13], v[192:195], v[240:243], v[10:13]
	v_mfma_f32_16x16x32_bf16 v[6:9], v[184:187], v[248:251], v[6:9]
	v_mfma_f32_16x16x32_bf16 v[2:5], v[192:195], v[248:251], v[2:5]
	s_barrier
	s_add_i32 s46, 0, 0x18000
	v_add_u32_e32 v163, s46, v159
	s_add_i32 s47, 0, 0x1c000
	ds_read_b128 v[164:167], v163
	ds_read_b128 v[168:171], v163 offset:1024
	ds_read_b128 v[172:175], v163 offset:2048
	ds_read_b128 v[176:179], v163 offset:3072
	v_add_u32_e32 v163, s47, v159
	ds_read_b128 v[180:183], v163
	ds_read_b128 v[184:187], v163 offset:1024
	ds_read_b128 v[188:191], v163 offset:2048
	ds_read_b128 v[192:195], v163 offset:3072
	s_add_u32 s24, s24, 0x40000
	s_addc_u32 s25, s25, 0
	s_mov_b32 m0, s34
	v_lshl_add_u64 v[230:231], s[24:25], 0, v[136:137]
	ds_read_b128 v[196:199], v162 offset:32768
	ds_read_b128 v[200:203], v162 offset:33792
	ds_read_b128 v[204:207], v162 offset:34816
	ds_read_b128 v[220:223], v162 offset:35840
	ds_read_b128 v[236:239], v162 offset:36864
	ds_read_b128 v[240:243], v162 offset:37888
	ds_read_b128 v[244:247], v162 offset:38912
	ds_read_b128 v[248:251], v162 offset:39936
	global_load_lds_dwordx4 v[230:231], off
	s_mov_b32 m0, s35
	v_lshl_add_u64 v[230:231], s[24:25], 0, v[132:133]
	global_load_lds_dwordx4 v[230:231], off
	s_branch .Lpadj_22
	s_nop 0
	s_nop 0
	s_nop 0
	s_nop 0
	s_nop 0
	s_nop 0
	s_nop 0
	s_nop 0
.Lpadj_22:
	s_waitcnt vmcnt(8)
	s_waitcnt lgkmcnt(0)
	s_barrier
	v_mfma_f32_16x16x32_bf16 v[126:129], v[164:167], v[196:199], v[126:129]
	v_mfma_f32_16x16x32_bf16 v[122:125], v[172:175], v[196:199], v[122:125]
	v_mfma_f32_16x16x32_bf16 v[118:121], v[164:167], v[204:207], v[118:121]
	v_mfma_f32_16x16x32_bf16 v[114:117], v[172:175], v[204:207], v[114:117]
	v_mfma_f32_16x16x32_bf16 v[110:113], v[164:167], v[236:239], v[110:113]
	v_mfma_f32_16x16x32_bf16 v[106:109], v[172:175], v[236:239], v[106:109]
	v_mfma_f32_16x16x32_bf16 v[102:105], v[164:167], v[244:247], v[102:105]
	v_mfma_f32_16x16x32_bf16 v[98:101], v[172:175], v[244:247], v[98:101]
	v_mfma_f32_16x16x32_bf16 v[126:129], v[168:171], v[200:203], v[126:129]
	v_mfma_f32_16x16x32_bf16 v[122:125], v[176:179], v[200:203], v[122:125]
	v_mfma_f32_16x16x32_bf16 v[118:121], v[168:171], v[220:223], v[118:121]
	v_mfma_f32_16x16x32_bf16 v[114:117], v[176:179], v[220:223], v[114:117]
	v_mfma_f32_16x16x32_bf16 v[110:113], v[168:171], v[240:243], v[110:113]
	v_mfma_f32_16x16x32_bf16 v[106:109], v[176:179], v[240:243], v[106:109]
	v_mfma_f32_16x16x32_bf16 v[102:105], v[168:171], v[248:251], v[102:105]
	v_mfma_f32_16x16x32_bf16 v[98:101], v[176:179], v[248:251], v[98:101]
	v_mfma_f32_16x16x32_bf16 v[94:97], v[180:183], v[196:199], v[94:97]
	v_mfma_f32_16x16x32_bf16 v[90:93], v[188:191], v[196:199], v[90:93]
	v_mfma_f32_16x16x32_bf16 v[86:89], v[180:183], v[204:207], v[86:89]
	v_mfma_f32_16x16x32_bf16 v[82:85], v[188:191], v[204:207], v[82:85]
	v_mfma_f32_16x16x32_bf16 v[78:81], v[180:183], v[236:239], v[78:81]
	v_mfma_f32_16x16x32_bf16 v[74:77], v[188:191], v[236:239], v[74:77]
	v_mfma_f32_16x16x32_bf16 v[70:73], v[180:183], v[244:247], v[70:73]
	v_mfma_f32_16x16x32_bf16 v[66:69], v[188:191], v[244:247], v[66:69]
	v_mfma_f32_16x16x32_bf16 v[94:97], v[184:187], v[200:203], v[94:97]
	v_mfma_f32_16x16x32_bf16 v[90:93], v[192:195], v[200:203], v[90:93]
	v_mfma_f32_16x16x32_bf16 v[86:89], v[184:187], v[220:223], v[86:89]
	v_mfma_f32_16x16x32_bf16 v[82:85], v[192:195], v[220:223], v[82:85]
	v_mfma_f32_16x16x32_bf16 v[78:81], v[184:187], v[240:243], v[78:81]
	v_mfma_f32_16x16x32_bf16 v[74:77], v[192:195], v[240:243], v[74:77]
	v_mfma_f32_16x16x32_bf16 v[70:73], v[184:187], v[248:251], v[70:73]
	v_mfma_f32_16x16x32_bf16 v[66:69], v[192:195], v[248:251], v[66:69]
	s_barrier
	s_add_i32 s24, s46, s28
	v_lshl_add_u64 v[150:151], v[150:151], 0, s[96:97]
	s_mov_b32 m0, s24
	ds_read_b128 v[196:199], v162 offset:49152
	ds_read_b128 v[200:203], v162 offset:50176
	ds_read_b128 v[204:207], v162 offset:51200
	ds_read_b128 v[220:223], v162 offset:52224
	ds_read_b128 v[236:239], v162 offset:53248
	ds_read_b128 v[240:243], v162 offset:54272
	ds_read_b128 v[244:247], v162 offset:55296
	ds_read_b128 v[248:251], v162 offset:56320
	global_load_lds_dwordx4 v[150:151], off
	s_add_i32 m0, s24, 0x2000
	s_add_u32 s22, s22, 0x40080
	v_lshl_add_u64 v[150:151], v[208:209], 0, s[96:97]
	s_addc_u32 s23, s23, 0
	s_add_i32 s24, s47, s28
	global_load_lds_dwordx4 v[150:151], off
	s_mov_b32 m0, s24
	v_lshl_add_u64 v[150:151], s[22:23], 0, v[134:135]
	global_load_lds_dwordx4 v[150:151], off
	s_add_i32 m0, s24, 0x2000
	v_lshl_add_u64 v[150:151], s[22:23], 0, v[130:131]
	global_load_lds_dwordx4 v[150:151], off
	s_mov_b32 m0, s36
	v_lshl_add_u64 v[150:151], v[224:225], 0, s[96:97]
	global_load_lds_dwordx4 v[150:151], off
	s_mov_b32 m0, s37
	v_lshl_add_u64 v[150:151], v[252:253], 0, s[96:97]
	global_load_lds_dwordx4 v[150:151], off
	s_branch .Lpadj_23
	s_nop 0
	s_nop 0
	s_nop 0
	s_nop 0
	s_nop 0
	s_nop 0
.Lpadj_23:
	s_waitcnt vmcnt(8)
	s_waitcnt lgkmcnt(0)
	s_barrier
	v_mfma_f32_16x16x32_bf16 v[62:65], v[164:167], v[196:199], v[62:65]
	v_mfma_f32_16x16x32_bf16 v[58:61], v[172:175], v[196:199], v[58:61]
	v_mfma_f32_16x16x32_bf16 v[54:57], v[164:167], v[204:207], v[54:57]
	v_mfma_f32_16x16x32_bf16 v[50:53], v[172:175], v[204:207], v[50:53]
	v_mfma_f32_16x16x32_bf16 v[46:49], v[164:167], v[236:239], v[46:49]
	v_mfma_f32_16x16x32_bf16 v[42:45], v[172:175], v[236:239], v[42:45]
	v_mfma_f32_16x16x32_bf16 v[38:41], v[164:167], v[244:247], v[38:41]
	v_mfma_f32_16x16x32_bf16 v[34:37], v[172:175], v[244:247], v[34:37]
	v_mfma_f32_16x16x32_bf16 v[62:65], v[168:171], v[200:203], v[62:65]
	v_mfma_f32_16x16x32_bf16 v[58:61], v[176:179], v[200:203], v[58:61]
	v_mfma_f32_16x16x32_bf16 v[54:57], v[168:171], v[220:223], v[54:57]
	v_mfma_f32_16x16x32_bf16 v[50:53], v[176:179], v[220:223], v[50:53]
	v_mfma_f32_16x16x32_bf16 v[46:49], v[168:171], v[240:243], v[46:49]
	v_mfma_f32_16x16x32_bf16 v[42:45], v[176:179], v[240:243], v[42:45]
	v_mfma_f32_16x16x32_bf16 v[38:41], v[168:171], v[248:251], v[38:41]
	v_mfma_f32_16x16x32_bf16 v[34:37], v[176:179], v[248:251], v[34:37]
	v_mfma_f32_16x16x32_bf16 v[30:33], v[180:183], v[196:199], v[30:33]
	v_mfma_f32_16x16x32_bf16 v[26:29], v[188:191], v[196:199], v[26:29]
	v_mfma_f32_16x16x32_bf16 v[22:25], v[180:183], v[204:207], v[22:25]
	v_mfma_f32_16x16x32_bf16 v[18:21], v[188:191], v[204:207], v[18:21]
	v_mfma_f32_16x16x32_bf16 v[14:17], v[180:183], v[236:239], v[14:17]
	v_mfma_f32_16x16x32_bf16 v[10:13], v[188:191], v[236:239], v[10:13]
	v_mfma_f32_16x16x32_bf16 v[6:9], v[180:183], v[244:247], v[6:9]
	v_mfma_f32_16x16x32_bf16 v[2:5], v[188:191], v[244:247], v[2:5]
	v_mfma_f32_16x16x32_bf16 v[30:33], v[184:187], v[200:203], v[30:33]
	v_mfma_f32_16x16x32_bf16 v[26:29], v[192:195], v[200:203], v[26:29]
	v_mfma_f32_16x16x32_bf16 v[22:25], v[184:187], v[220:223], v[22:25]
	v_mfma_f32_16x16x32_bf16 v[18:21], v[192:195], v[220:223], v[18:21]
	v_mfma_f32_16x16x32_bf16 v[14:17], v[184:187], v[240:243], v[14:17]
	v_mfma_f32_16x16x32_bf16 v[10:13], v[192:195], v[240:243], v[10:13]
	v_mfma_f32_16x16x32_bf16 v[6:9], v[184:187], v[248:251], v[6:9]
	v_mfma_f32_16x16x32_bf16 v[2:5], v[192:195], v[248:251], v[2:5]
	s_barrier
	s_add_i32 s45, s45, 2
	s_add_u32 s43, s43, 0x100
	s_addc_u32 s44, s44, 0
	s_add_u32 s20, s20, 0x100
	s_addc_u32 s21, s21, 0
	s_cmp_gt_u32 s45, 13
.LBB0_640:
	s_add_u32 s22, s20, 0xfffc0080
	s_addc_u32 s23, s21, -1
	s_add_i32 s46, 0, 0x10000
	s_cmp_eq_u32 s45, 12
	s_cselect_b32 s25, s13, s23
	s_cselect_b32 s24, s19, s22
	v_add_u32_e32 v150, s46, v159
	s_cselect_b32 s23, s11, s44
	s_cselect_b32 s22, s41, s43
	s_add_i32 s48, 0, 0x14000
	ds_read_b128 v[164:167], v150
	ds_read_b128 v[168:171], v150 offset:1024
	ds_read_b128 v[172:175], v150 offset:2048
	ds_read_b128 v[176:179], v150 offset:3072
	v_add_u32_e32 v150, s48, v159
	ds_read_b128 v[180:183], v150
	ds_read_b128 v[184:187], v150 offset:1024
	ds_read_b128 v[188:191], v150 offset:2048
	ds_read_b128 v[192:195], v150 offset:3072
	v_lshl_add_u64 v[150:151], s[20:21], 0, v[140:141]
	s_add_i32 m0, s30, 0xc000
	ds_read_b128 v[196:199], v162
	ds_read_b128 v[200:203], v162 offset:1024
	ds_read_b128 v[204:207], v162 offset:2048
	ds_read_b128 v[220:223], v162 offset:3072
	ds_read_b128 v[236:239], v162 offset:4096
	ds_read_b128 v[240:243], v162 offset:5120
	ds_read_b128 v[244:247], v162 offset:6144
	ds_read_b128 v[248:251], v162 offset:7168
	global_load_lds_dwordx4 v[150:151], off
	s_add_i32 m0, s30, 0xe000
	v_lshl_add_u64 v[150:151], s[20:21], 0, v[138:139]
	global_load_lds_dwordx4 v[150:151], off
	s_branch .Lpadj_24
	s_nop 0
	s_nop 0
	s_nop 0
	s_nop 0
	s_nop 0
	s_nop 0
	s_nop 0
	s_nop 0
	s_nop 0
.Lpadj_24:
	s_waitcnt vmcnt(8)
	s_waitcnt lgkmcnt(0)
	s_barrier
	v_mfma_f32_16x16x32_bf16 v[126:129], v[164:167], v[196:199], v[126:129]
	v_mfma_f32_16x16x32_bf16 v[122:125], v[172:175], v[196:199], v[122:125]
	v_mfma_f32_16x16x32_bf16 v[118:121], v[164:167], v[204:207], v[118:121]
	v_mfma_f32_16x16x32_bf16 v[114:117], v[172:175], v[204:207], v[114:117]
	v_mfma_f32_16x16x32_bf16 v[110:113], v[164:167], v[236:239], v[110:113]
	v_mfma_f32_16x16x32_bf16 v[106:109], v[172:175], v[236:239], v[106:109]
	v_mfma_f32_16x16x32_bf16 v[102:105], v[164:167], v[244:247], v[102:105]
	v_mfma_f32_16x16x32_bf16 v[98:101], v[172:175], v[244:247], v[98:101]
	v_mfma_f32_16x16x32_bf16 v[126:129], v[168:171], v[200:203], v[126:129]
	v_mfma_f32_16x16x32_bf16 v[122:125], v[176:179], v[200:203], v[122:125]
	v_mfma_f32_16x16x32_bf16 v[118:121], v[168:171], v[220:223], v[118:121]
	v_mfma_f32_16x16x32_bf16 v[114:117], v[176:179], v[220:223], v[114:117]
	v_mfma_f32_16x16x32_bf16 v[110:113], v[168:171], v[240:243], v[110:113]
	v_mfma_f32_16x16x32_bf16 v[106:109], v[176:179], v[240:243], v[106:109]
	v_mfma_f32_16x16x32_bf16 v[102:105], v[168:171], v[248:251], v[102:105]
	v_mfma_f32_16x16x32_bf16 v[98:101], v[176:179], v[248:251], v[98:101]
	v_mfma_f32_16x16x32_bf16 v[94:97], v[180:183], v[196:199], v[94:97]
	v_mfma_f32_16x16x32_bf16 v[90:93], v[188:191], v[196:199], v[90:93]
	v_mfma_f32_16x16x32_bf16 v[86:89], v[180:183], v[204:207], v[86:89]
	v_mfma_f32_16x16x32_bf16 v[82:85], v[188:191], v[204:207], v[82:85]
	v_mfma_f32_16x16x32_bf16 v[78:81], v[180:183], v[236:239], v[78:81]
	v_mfma_f32_16x16x32_bf16 v[74:77], v[188:191], v[236:239], v[74:77]
	v_mfma_f32_16x16x32_bf16 v[70:73], v[180:183], v[244:247], v[70:73]
	v_mfma_f32_16x16x32_bf16 v[66:69], v[188:191], v[244:247], v[66:69]
	v_mfma_f32_16x16x32_bf16 v[94:97], v[184:187], v[200:203], v[94:97]
	v_mfma_f32_16x16x32_bf16 v[90:93], v[192:195], v[200:203], v[90:93]
	v_mfma_f32_16x16x32_bf16 v[86:89], v[184:187], v[220:223], v[86:89]
	v_mfma_f32_16x16x32_bf16 v[82:85], v[192:195], v[220:223], v[82:85]
	v_mfma_f32_16x16x32_bf16 v[78:81], v[184:187], v[240:243], v[78:81]
	v_mfma_f32_16x16x32_bf16 v[74:77], v[192:195], v[240:243], v[74:77]
	v_mfma_f32_16x16x32_bf16 v[70:73], v[184:187], v[248:251], v[70:73]
	v_mfma_f32_16x16x32_bf16 v[66:69], v[192:195], v[248:251], v[66:69]
	s_barrier
	s_add_i32 s46, s46, s28
	v_lshl_add_u64 v[150:151], s[22:23], 0, v[134:135]
	s_mov_b32 m0, s46
	ds_read_b128 v[196:199], v162 offset:16384
	ds_read_b128 v[200:203], v162 offset:17408
	ds_read_b128 v[204:207], v162 offset:18432
	ds_read_b128 v[220:223], v162 offset:19456
	ds_read_b128 v[236:239], v162 offset:20480
	ds_read_b128 v[240:243], v162 offset:21504
	ds_read_b128 v[244:247], v162 offset:22528
	ds_read_b128 v[248:251], v162 offset:23552
	global_load_lds_dwordx4 v[150:151], off
	s_add_i32 m0, s46, 0x2000
	s_add_u32 s46, s22, 0x40000
	v_lshl_add_u64 v[208:209], s[22:23], 0, v[130:131]
	s_addc_u32 s47, s23, 0
	s_add_i32 s48, s48, s28
	global_load_lds_dwordx4 v[208:209], off
	v_lshl_add_u64 v[224:225], s[46:47], 0, v[134:135]
	s_mov_b32 m0, s48
	v_lshl_add_u64 v[252:253], s[24:25], 0, v[132:133]
	global_load_lds_dwordx4 v[224:225], off
	s_add_i32 m0, s48, 0x2000
	v_lshl_add_u64 v[224:225], s[46:47], 0, v[130:131]
	global_load_lds_dwordx4 v[224:225], off
	s_mov_b32 m0, s30
	v_lshl_add_u64 v[224:225], s[24:25], 0, v[136:137]
	global_load_lds_dwordx4 v[224:225], off
	s_mov_b32 m0, s31
	s_nop 0
	global_load_lds_dwordx4 v[252:253], off
	s_branch .Lpadj_25
	s_nop 0
	s_nop 0
	s_nop 0
	s_nop 0
	s_nop 0
.Lpadj_25:
	s_waitcnt vmcnt(8)
	s_waitcnt lgkmcnt(0)
	s_barrier
	v_mfma_f32_16x16x32_bf16 v[62:65], v[164:167], v[196:199], v[62:65]
	v_mfma_f32_16x16x32_bf16 v[58:61], v[172:175], v[196:199], v[58:61]
	v_mfma_f32_16x16x32_bf16 v[54:57], v[164:167], v[204:207], v[54:57]
	v_mfma_f32_16x16x32_bf16 v[50:53], v[172:175], v[204:207], v[50:53]
	v_mfma_f32_16x16x32_bf16 v[46:49], v[164:167], v[236:239], v[46:49]
	v_mfma_f32_16x16x32_bf16 v[42:45], v[172:175], v[236:239], v[42:45]
	v_mfma_f32_16x16x32_bf16 v[38:41], v[164:167], v[244:247], v[38:41]
	v_mfma_f32_16x16x32_bf16 v[34:37], v[172:175], v[244:247], v[34:37]
	v_mfma_f32_16x16x32_bf16 v[62:65], v[168:171], v[200:203], v[62:65]
	v_mfma_f32_16x16x32_bf16 v[58:61], v[176:179], v[200:203], v[58:61]
	v_mfma_f32_16x16x32_bf16 v[54:57], v[168:171], v[220:223], v[54:57]
	v_mfma_f32_16x16x32_bf16 v[50:53], v[176:179], v[220:223], v[50:53]
	v_mfma_f32_16x16x32_bf16 v[46:49], v[168:171], v[240:243], v[46:49]
	v_mfma_f32_16x16x32_bf16 v[42:45], v[176:179], v[240:243], v[42:45]
	v_mfma_f32_16x16x32_bf16 v[38:41], v[168:171], v[248:251], v[38:41]
	v_mfma_f32_16x16x32_bf16 v[34:37], v[176:179], v[248:251], v[34:37]
	v_mfma_f32_16x16x32_bf16 v[30:33], v[180:183], v[196:199], v[30:33]
	v_mfma_f32_16x16x32_bf16 v[26:29], v[188:191], v[196:199], v[26:29]
	v_mfma_f32_16x16x32_bf16 v[22:25], v[180:183], v[204:207], v[22:25]
	v_mfma_f32_16x16x32_bf16 v[18:21], v[188:191], v[204:207], v[18:21]
	v_mfma_f32_16x16x32_bf16 v[14:17], v[180:183], v[236:239], v[14:17]
	v_mfma_f32_16x16x32_bf16 v[10:13], v[188:191], v[236:239], v[10:13]
	v_mfma_f32_16x16x32_bf16 v[6:9], v[180:183], v[244:247], v[6:9]
	v_mfma_f32_16x16x32_bf16 v[2:5], v[188:191], v[244:247], v[2:5]
	v_mfma_f32_16x16x32_bf16 v[30:33], v[184:187], v[200:203], v[30:33]
	v_mfma_f32_16x16x32_bf16 v[26:29], v[192:195], v[200:203], v[26:29]
	v_mfma_f32_16x16x32_bf16 v[22:25], v[184:187], v[220:223], v[22:25]
	v_mfma_f32_16x16x32_bf16 v[18:21], v[192:195], v[220:223], v[18:21]
	v_mfma_f32_16x16x32_bf16 v[14:17], v[184:187], v[240:243], v[14:17]
	v_mfma_f32_16x16x32_bf16 v[10:13], v[192:195], v[240:243], v[10:13]
	v_mfma_f32_16x16x32_bf16 v[6:9], v[184:187], v[248:251], v[6:9]
	v_mfma_f32_16x16x32_bf16 v[2:5], v[192:195], v[248:251], v[2:5]
	s_barrier
	s_add_i32 s46, 0, 0x18000
	v_add_u32_e32 v163, s46, v159
	s_add_i32 s47, 0, 0x1c000
	ds_read_b128 v[164:167], v163
	ds_read_b128 v[168:171], v163 offset:1024
	ds_read_b128 v[172:175], v163 offset:2048
	ds_read_b128 v[176:179], v163 offset:3072
	v_add_u32_e32 v163, s47, v159
	ds_read_b128 v[180:183], v163
	ds_read_b128 v[184:187], v163 offset:1024
	ds_read_b128 v[188:191], v163 offset:2048
	ds_read_b128 v[192:195], v163 offset:3072
	s_add_u32 s24, s24, 0x40000
	s_addc_u32 s25, s25, 0
	s_mov_b32 m0, s34
	v_lshl_add_u64 v[230:231], s[24:25], 0, v[136:137]
	ds_read_b128 v[196:199], v162 offset:32768
	ds_read_b128 v[200:203], v162 offset:33792
	ds_read_b128 v[204:207], v162 offset:34816
	ds_read_b128 v[220:223], v162 offset:35840
	ds_read_b128 v[236:239], v162 offset:36864
	ds_read_b128 v[240:243], v162 offset:37888
	ds_read_b128 v[244:247], v162 offset:38912
	ds_read_b128 v[248:251], v162 offset:39936
	global_load_lds_dwordx4 v[230:231], off
	s_mov_b32 m0, s35
	v_lshl_add_u64 v[230:231], s[24:25], 0, v[132:133]
	global_load_lds_dwordx4 v[230:231], off
	s_branch .Lpadj_26
	s_nop 0
	s_nop 0
	s_nop 0
	s_nop 0
	s_nop 0
	s_nop 0
	s_nop 0
	s_nop 0

.Lpadj_27:
	s_waitcnt vmcnt(8)
	s_waitcnt lgkmcnt(0)
	s_barrier
	v_mfma_f32_16x16x32_bf16 v[62:65], v[164:167], v[196:199], v[62:65]
	v_mfma_f32_16x16x32_bf16 v[58:61], v[172:175], v[196:199], v[58:61]
	v_mfma_f32_16x16x32_bf16 v[54:57], v[164:167], v[204:207], v[54:57]
	v_mfma_f32_16x16x32_bf16 v[50:53], v[172:175], v[204:207], v[50:53]
	v_mfma_f32_16x16x32_bf16 v[46:49], v[164:167], v[236:239], v[46:49]
	v_mfma_f32_16x16x32_bf16 v[42:45], v[172:175], v[236:239], v[42:45]
	v_mfma_f32_16x16x32_bf16 v[38:41], v[164:167], v[244:247], v[38:41]
	v_mfma_f32_16x16x32_bf16 v[34:37], v[172:175], v[244:247], v[34:37]
	v_mfma_f32_16x16x32_bf16 v[62:65], v[168:171], v[200:203], v[62:65]
	v_mfma_f32_16x16x32_bf16 v[58:61], v[176:179], v[200:203], v[58:61]
	v_mfma_f32_16x16x32_bf16 v[54:57], v[168:171], v[220:223], v[54:57]
	v_mfma_f32_16x16x32_bf16 v[50:53], v[176:179], v[220:223], v[50:53]
	v_mfma_f32_16x16x32_bf16 v[46:49], v[168:171], v[240:243], v[46:49]
	v_mfma_f32_16x16x32_bf16 v[42:45], v[176:179], v[240:243], v[42:45]
	v_mfma_f32_16x16x32_bf16 v[38:41], v[168:171], v[248:251], v[38:41]
	v_mfma_f32_16x16x32_bf16 v[34:37], v[176:179], v[248:251], v[34:37]
	v_mfma_f32_16x16x32_bf16 v[30:33], v[180:183], v[196:199], v[30:33]
	v_mfma_f32_16x16x32_bf16 v[26:29], v[188:191], v[196:199], v[26:29]
	v_mfma_f32_16x16x32_bf16 v[22:25], v[180:183], v[204:207], v[22:25]
	v_mfma_f32_16x16x32_bf16 v[18:21], v[188:191], v[204:207], v[18:21]
	v_mfma_f32_16x16x32_bf16 v[14:17], v[180:183], v[236:239], v[14:17]
	v_mfma_f32_16x16x32_bf16 v[10:13], v[188:191], v[236:239], v[10:13]
	v_mfma_f32_16x16x32_bf16 v[6:9], v[180:183], v[244:247], v[6:9]
	v_mfma_f32_16x16x32_bf16 v[2:5], v[188:191], v[244:247], v[2:5]
	v_mfma_f32_16x16x32_bf16 v[30:33], v[184:187], v[200:203], v[30:33]
	v_mfma_f32_16x16x32_bf16 v[26:29], v[192:195], v[200:203], v[26:29]
	v_mfma_f32_16x16x32_bf16 v[22:25], v[184:187], v[220:223], v[22:25]
	v_mfma_f32_16x16x32_bf16 v[18:21], v[192:195], v[220:223], v[18:21]
	v_mfma_f32_16x16x32_bf16 v[14:17], v[184:187], v[240:243], v[14:17]
	v_mfma_f32_16x16x32_bf16 v[10:13], v[192:195], v[240:243], v[10:13]
	v_mfma_f32_16x16x32_bf16 v[6:9], v[184:187], v[248:251], v[6:9]
	v_mfma_f32_16x16x32_bf16 v[2:5], v[192:195], v[248:251], v[2:5]
	s_barrier
	s_add_i32 s45, s45, 2
	s_add_u32 s43, s43, 0x100
	s_addc_u32 s44, s44, 0
	s_add_u32 s20, s20, 0x100
	s_addc_u32 s21, s21, 0
	s_cmp_gt_u32 s45, 13
	s_cbranch_scc0 .LBB0_640
	s_and_b64 vcc, exec, s[8:9]
	s_cbranch_vccz .LBB0_643
	s_barrier
